# packed f32 VALU ops in the inproj epilogues split into scalar pairs
# speedup vs baseline: 1.0062x; 1.0015x over previous
.Lmy_ip0_epi:
	s_cbranch_scc1 .LBB0_175
	v_mul_f32_e32 v64, 0xbfb8aa3b, v2
	v_mul_f32_e32 v65, 0xbfb8aa3b, v3
	v_exp_f32_e32 v64, v64
	v_exp_f32_e32 v65, v65
	v_mul_f32_e32 v66, 0xbfb8aa3b, v0
	v_mul_f32_e32 v67, 0xbfb8aa3b, v1
	v_exp_f32_e32 v66, v66
	v_add_f32_e32 v64, 1.0, v64
	v_add_f32_e32 v65, 1.0, v65
	v_exp_f32_e32 v67, v67
	v_div_scale_f32 v70, s[4:5], v65, v65, v3
	v_rcp_f32_e32 v71, v70
	v_add_f32_e32 v68, 1.0, v66
	v_add_f32_e32 v69, 1.0, v67
	v_mul_f32_e32 v73, 0xbfb8aa3b, v5
	v_exp_f32_e32 v73, v73
	v_fma_f32 v66, -v70, v71, 1.0
	v_fmac_f32_e32 v71, v66, v71
	v_div_scale_f32 v66, vcc, v3, v65, v3
	v_mul_f32_e32 v67, v66, v71
	v_fma_f32 v72, -v70, v67, v66
	v_fmac_f32_e32 v67, v72, v71
	v_fma_f32 v66, -v70, v67, v66
	v_div_scale_f32 v70, s[4:5], v64, v64, v2
	v_rcp_f32_e32 v72, v70
	v_div_fmas_f32 v66, v66, v71, v67
	v_div_fixup_f32 v67, v66, v65, v3
	v_mul_f32_e32 v81, 0xbfb8aa3b, v13
	v_fma_f32 v65, -v70, v72, 1.0
	v_fmac_f32_e32 v72, v65, v72
	v_div_scale_f32 v65, vcc, v2, v64, v2
	v_mul_f32_e32 v66, v65, v72
	v_fma_f32 v71, -v70, v66, v65
	v_fmac_f32_e32 v66, v71, v72
	v_fma_f32 v65, -v70, v66, v65
	v_div_scale_f32 v70, s[4:5], v69, v69, v1
	v_rcp_f32_e32 v71, v70
	v_div_fmas_f32 v65, v65, v72, v66
	v_div_fixup_f32 v66, v65, v64, v2
	v_exp_f32_e32 v81, v81
	v_fma_f32 v64, -v70, v71, 1.0
	v_fmac_f32_e32 v71, v64, v71
	v_div_scale_f32 v64, vcc, v1, v69, v1
	v_mul_f32_e32 v65, v64, v71
	v_fma_f32 v72, -v70, v65, v64
	v_fmac_f32_e32 v65, v72, v71
	v_fma_f32 v64, -v70, v65, v64
	v_div_scale_f32 v70, s[4:5], v68, v68, v0
	v_rcp_f32_e32 v74, v70
	v_div_fmas_f32 v64, v64, v71, v65
	v_div_fixup_f32 v65, v64, v69, v1
	v_mul_f32_e32 v72, 0xbfb8aa3b, v4
	v_fma_f32 v64, -v70, v74, 1.0
	v_fmac_f32_e32 v74, v64, v74
	v_div_scale_f32 v64, vcc, v0, v68, v0
	v_mul_f32_e32 v69, v64, v74
	v_fma_f32 v71, -v70, v69, v64
	v_fmac_f32_e32 v69, v71, v74
	v_fma_f32 v64, -v70, v69, v64
	v_mul_f32_e32 v70, 0xbfb8aa3b, v6
	v_mul_f32_e32 v71, 0xbfb8aa3b, v7
	v_exp_f32_e32 v70, v70
	v_exp_f32_e32 v71, v71
	v_exp_f32_e32 v72, v72
	v_div_fmas_f32 v64, v64, v74, v69
	v_div_fixup_f32 v64, v64, v68, v0
	v_add_f32_e32 v70, 1.0, v70
	v_add_f32_e32 v71, 1.0, v71
	v_add_f32_e32 v68, 1.0, v72
	v_add_f32_e32 v69, 1.0, v73
	v_div_scale_f32 v75, s[4:5], v71, v71, v7
	v_rcp_f32_e32 v76, v75
	v_mul_f32_e32 v89, 0xbfb8aa3b, v21
	v_exp_f32_e32 v89, v89
	v_mul_f32_e32 v97, 0xbfb8aa3b, v29
	v_fma_f32 v72, -v75, v76, 1.0
	v_fmac_f32_e32 v76, v72, v76
	v_div_scale_f32 v72, vcc, v7, v71, v7
	v_mul_f32_e32 v73, v72, v76
	v_fma_f32 v74, -v75, v73, v72
	v_fmac_f32_e32 v73, v74, v76
	v_div_scale_f32 v74, s[4:5], v70, v70, v6
	v_fma_f32 v72, -v75, v73, v72
	v_rcp_f32_e32 v75, v74
	v_div_fmas_f32 v72, v72, v76, v73
	v_div_fixup_f32 v71, v72, v71, v7
	v_exp_f32_e32 v97, v97
	v_fma_f32 v72, -v74, v75, 1.0
	v_fmac_f32_e32 v75, v72, v75
	v_div_scale_f32 v72, vcc, v6, v70, v6
	v_mul_f32_e32 v73, v72, v75
	v_fma_f32 v76, -v74, v73, v72
	v_fmac_f32_e32 v73, v76, v75
	v_fma_f32 v72, -v74, v73, v72
	v_div_scale_f32 v74, s[4:5], v69, v69, v5
	v_rcp_f32_e32 v76, v74
	v_div_fmas_f32 v72, v72, v75, v73
	v_div_fixup_f32 v70, v72, v70, v6
	v_mul_f32_e32 v105, 0xbfb8aa3b, v37
	v_fma_f32 v72, -v74, v76, 1.0
	v_fmac_f32_e32 v76, v72, v76
	v_div_scale_f32 v72, vcc, v5, v69, v5
	v_mul_f32_e32 v73, v72, v76
	v_fma_f32 v75, -v74, v73, v72
	v_fmac_f32_e32 v73, v75, v76
	v_fma_f32 v72, -v74, v73, v72
	v_div_scale_f32 v74, s[4:5], v68, v68, v4
	v_rcp_f32_e32 v77, v74
	v_div_fmas_f32 v72, v72, v76, v73
	v_div_fixup_f32 v69, v72, v69, v5
	v_mul_f32_e32 v75, 0xbfb8aa3b, v9
	v_fma_f32 v72, -v74, v77, 1.0
	v_fmac_f32_e32 v77, v72, v77
	v_div_scale_f32 v72, vcc, v4, v68, v4
	v_mul_f32_e32 v76, v72, v77
	v_fma_f32 v73, -v74, v76, v72
	v_fmac_f32_e32 v76, v73, v77
	v_fma_f32 v78, -v74, v76, v72
	v_mul_f32_e32 v72, 0xbfb8aa3b, v10
	v_mul_f32_e32 v73, 0xbfb8aa3b, v11
	v_exp_f32_e32 v72, v72
	v_exp_f32_e32 v73, v73
	v_mul_f32_e32 v74, 0xbfb8aa3b, v8
	v_exp_f32_e32 v74, v74
	v_exp_f32_e32 v75, v75
	v_add_f32_e32 v72, 1.0, v72
	v_add_f32_e32 v73, 1.0, v73
	v_div_fmas_f32 v76, v78, v77, v76
	v_div_scale_f32 v79, s[4:5], v73, v73, v11
	v_rcp_f32_e32 v80, v79
	v_div_fixup_f32 v68, v76, v68, v4
	v_add_f32_e32 v76, 1.0, v74
	v_add_f32_e32 v77, 1.0, v75
	v_exp_f32_e32 v105, v105
	v_fma_f32 v74, -v79, v80, 1.0
	v_fmac_f32_e32 v80, v74, v80
	v_div_scale_f32 v74, vcc, v11, v73, v11
	v_mul_f32_e32 v75, v74, v80
	v_fma_f32 v78, -v79, v75, v74
	v_fmac_f32_e32 v75, v78, v80
	v_div_scale_f32 v78, s[4:5], v72, v72, v10
	v_fma_f32 v74, -v79, v75, v74
	v_rcp_f32_e32 v79, v78
	v_div_fmas_f32 v74, v74, v80, v75
	v_div_fixup_f32 v75, v74, v73, v11
	v_mul_f32_e32 v113, 0xbfb8aa3b, v45
	v_fma_f32 v73, -v78, v79, 1.0
	v_fmac_f32_e32 v79, v73, v79
	v_div_scale_f32 v73, vcc, v10, v72, v10
	v_mul_f32_e32 v74, v73, v79
	v_fma_f32 v80, -v78, v74, v73
	v_fmac_f32_e32 v74, v80, v79
	v_fma_f32 v73, -v78, v74, v73
	v_div_scale_f32 v78, s[4:5], v77, v77, v9
	v_rcp_f32_e32 v80, v78
	v_div_fmas_f32 v73, v73, v79, v74
	v_div_fixup_f32 v74, v73, v72, v10
	v_exp_f32_e32 v113, v113
	v_fma_f32 v72, -v78, v80, 1.0
	v_fmac_f32_e32 v80, v72, v80
	v_div_scale_f32 v72, vcc, v9, v77, v9
	v_mul_f32_e32 v73, v72, v80
	v_fma_f32 v79, -v78, v73, v72
	v_fmac_f32_e32 v73, v79, v80
	v_fma_f32 v72, -v78, v73, v72
	v_div_scale_f32 v78, s[4:5], v76, v76, v8
	v_rcp_f32_e32 v82, v78
	v_div_fmas_f32 v72, v72, v80, v73
	v_div_fixup_f32 v73, v72, v77, v9
	v_mul_f32_e32 v80, 0xbfb8aa3b, v12
	v_fma_f32 v72, -v78, v82, 1.0
	v_fmac_f32_e32 v82, v72, v82
	v_div_scale_f32 v72, vcc, v8, v76, v8
	v_mul_f32_e32 v77, v72, v82
	v_fma_f32 v79, -v78, v77, v72
	v_fmac_f32_e32 v77, v79, v82
	v_fma_f32 v72, -v78, v77, v72
	v_mul_f32_e32 v78, 0xbfb8aa3b, v14
	v_mul_f32_e32 v79, 0xbfb8aa3b, v15
	v_exp_f32_e32 v78, v78
	v_exp_f32_e32 v79, v79
	v_exp_f32_e32 v80, v80
	v_div_fmas_f32 v72, v72, v82, v77
	v_div_fixup_f32 v72, v72, v76, v8
	v_add_f32_e32 v78, 1.0, v78
	v_add_f32_e32 v79, 1.0, v79
	v_add_f32_e32 v76, 1.0, v80
	v_add_f32_e32 v77, 1.0, v81
	v_div_scale_f32 v83, s[4:5], v79, v79, v15
	v_rcp_f32_e32 v84, v83
	v_mul_f32_e32 v121, 0xbfb8aa3b, v53
	v_exp_f32_e32 v121, v121
	s_mov_b64 s[6:7], 0
	v_fma_f32 v80, -v83, v84, 1.0
	v_fmac_f32_e32 v84, v80, v84
	v_div_scale_f32 v80, vcc, v15, v79, v15
	v_mul_f32_e32 v81, v80, v84
	v_fma_f32 v82, -v83, v81, v80
	v_fmac_f32_e32 v81, v82, v84
	v_div_scale_f32 v82, s[4:5], v78, v78, v14
	v_fma_f32 v80, -v83, v81, v80
	v_rcp_f32_e32 v83, v82
	v_div_fmas_f32 v80, v80, v84, v81
	v_div_fixup_f32 v79, v80, v79, v15
	v_fma_f32 v80, -v82, v83, 1.0
	v_fmac_f32_e32 v83, v80, v83
	v_div_scale_f32 v80, vcc, v14, v78, v14
	v_mul_f32_e32 v81, v80, v83
	v_fma_f32 v84, -v82, v81, v80
	v_fmac_f32_e32 v81, v84, v83
	v_fma_f32 v80, -v82, v81, v80
	v_div_scale_f32 v82, s[4:5], v77, v77, v13
	v_rcp_f32_e32 v84, v82
	v_div_fmas_f32 v80, v80, v83, v81
	v_div_fixup_f32 v78, v80, v78, v14
	v_fma_f32 v80, -v82, v84, 1.0
	v_fmac_f32_e32 v84, v80, v84
	v_div_scale_f32 v80, vcc, v13, v77, v13
	v_mul_f32_e32 v81, v80, v84
	v_fma_f32 v83, -v82, v81, v80
	v_fmac_f32_e32 v81, v83, v84
	v_fma_f32 v80, -v82, v81, v80
	v_div_scale_f32 v82, s[4:5], v76, v76, v12
	v_rcp_f32_e32 v85, v82
	v_div_fmas_f32 v80, v80, v84, v81
	v_div_fixup_f32 v77, v80, v77, v13
	v_mul_f32_e32 v83, 0xbfb8aa3b, v17
	v_fma_f32 v80, -v82, v85, 1.0
	v_fmac_f32_e32 v85, v80, v85
	v_div_scale_f32 v80, vcc, v12, v76, v12
	v_mul_f32_e32 v84, v80, v85
	v_fma_f32 v81, -v82, v84, v80
	v_fmac_f32_e32 v84, v81, v85
	v_fma_f32 v86, -v82, v84, v80
	v_mul_f32_e32 v80, 0xbfb8aa3b, v18
	v_mul_f32_e32 v81, 0xbfb8aa3b, v19
	v_exp_f32_e32 v80, v80
	v_exp_f32_e32 v81, v81
	v_mul_f32_e32 v82, 0xbfb8aa3b, v16
	v_exp_f32_e32 v82, v82
	v_exp_f32_e32 v83, v83
	v_add_f32_e32 v80, 1.0, v80
	v_add_f32_e32 v81, 1.0, v81
	v_div_fmas_f32 v84, v86, v85, v84
	v_div_scale_f32 v87, s[4:5], v81, v81, v19
	v_rcp_f32_e32 v88, v87
	v_div_fixup_f32 v76, v84, v76, v12
	v_add_f32_e32 v84, 1.0, v82
	v_add_f32_e32 v85, 1.0, v83
	v_fma_f32 v82, -v87, v88, 1.0
	v_fmac_f32_e32 v88, v82, v88
	v_div_scale_f32 v82, vcc, v19, v81, v19
	v_mul_f32_e32 v83, v82, v88
	v_fma_f32 v86, -v87, v83, v82
	v_fmac_f32_e32 v83, v86, v88
	v_div_scale_f32 v86, s[4:5], v80, v80, v18
	v_fma_f32 v82, -v87, v83, v82
	v_rcp_f32_e32 v87, v86
	v_div_fmas_f32 v82, v82, v88, v83
	v_div_fixup_f32 v83, v82, v81, v19
	v_fma_f32 v81, -v86, v87, 1.0
	v_fmac_f32_e32 v87, v81, v87
	v_div_scale_f32 v81, vcc, v18, v80, v18
	v_mul_f32_e32 v82, v81, v87
	v_fma_f32 v88, -v86, v82, v81
	v_fmac_f32_e32 v82, v88, v87
	v_fma_f32 v81, -v86, v82, v81
	v_div_scale_f32 v86, s[4:5], v85, v85, v17
	v_rcp_f32_e32 v88, v86
	v_div_fmas_f32 v81, v81, v87, v82
	v_div_fixup_f32 v82, v81, v80, v18
	v_fma_f32 v80, -v86, v88, 1.0
	v_fmac_f32_e32 v88, v80, v88
	v_div_scale_f32 v80, vcc, v17, v85, v17
	v_mul_f32_e32 v81, v80, v88
	v_fma_f32 v87, -v86, v81, v80
	v_fmac_f32_e32 v81, v87, v88
	v_fma_f32 v80, -v86, v81, v80
	v_div_scale_f32 v86, s[4:5], v84, v84, v16
	v_rcp_f32_e32 v90, v86
	v_div_fmas_f32 v80, v80, v88, v81
	v_div_fixup_f32 v81, v80, v85, v17
	v_mul_f32_e32 v88, 0xbfb8aa3b, v20
	v_fma_f32 v80, -v86, v90, 1.0
	v_fmac_f32_e32 v90, v80, v90
	v_div_scale_f32 v80, vcc, v16, v84, v16
	v_mul_f32_e32 v85, v80, v90
	v_fma_f32 v87, -v86, v85, v80
	v_fmac_f32_e32 v85, v87, v90
	v_fma_f32 v80, -v86, v85, v80
	v_mul_f32_e32 v86, 0xbfb8aa3b, v22
	v_mul_f32_e32 v87, 0xbfb8aa3b, v23
	v_exp_f32_e32 v86, v86
	v_exp_f32_e32 v87, v87
	v_exp_f32_e32 v88, v88
	v_div_fmas_f32 v80, v80, v90, v85
	v_div_fixup_f32 v80, v80, v84, v16
	v_add_f32_e32 v86, 1.0, v86
	v_add_f32_e32 v87, 1.0, v87
	v_add_f32_e32 v84, 1.0, v88
	v_add_f32_e32 v85, 1.0, v89
	v_div_scale_f32 v91, s[4:5], v87, v87, v23
	v_rcp_f32_e32 v92, v91
	s_nop 0
	v_fma_f32 v88, -v91, v92, 1.0
	v_fmac_f32_e32 v92, v88, v92
	v_div_scale_f32 v88, vcc, v23, v87, v23
	v_mul_f32_e32 v89, v88, v92
	v_fma_f32 v90, -v91, v89, v88
	v_fmac_f32_e32 v89, v90, v92
	v_div_scale_f32 v90, s[4:5], v86, v86, v22
	v_fma_f32 v88, -v91, v89, v88
	v_rcp_f32_e32 v91, v90
	v_div_fmas_f32 v88, v88, v92, v89
	v_div_fixup_f32 v87, v88, v87, v23
	v_fma_f32 v88, -v90, v91, 1.0
	v_fmac_f32_e32 v91, v88, v91
	v_div_scale_f32 v88, vcc, v22, v86, v22
	v_mul_f32_e32 v89, v88, v91
	v_fma_f32 v92, -v90, v89, v88
	v_fmac_f32_e32 v89, v92, v91
	v_fma_f32 v88, -v90, v89, v88
	v_div_scale_f32 v90, s[4:5], v85, v85, v21
	v_rcp_f32_e32 v92, v90
	v_div_fmas_f32 v88, v88, v91, v89
	v_div_fixup_f32 v86, v88, v86, v22
	v_fma_f32 v88, -v90, v92, 1.0
	v_fmac_f32_e32 v92, v88, v92
	v_div_scale_f32 v88, vcc, v21, v85, v21
	v_mul_f32_e32 v89, v88, v92
	v_fma_f32 v91, -v90, v89, v88
	v_fmac_f32_e32 v89, v91, v92
	v_fma_f32 v88, -v90, v89, v88
	v_div_scale_f32 v90, s[4:5], v84, v84, v20
	v_rcp_f32_e32 v93, v90
	v_div_fmas_f32 v88, v88, v92, v89
	v_div_fixup_f32 v85, v88, v85, v21
	v_mul_f32_e32 v91, 0xbfb8aa3b, v25
	v_fma_f32 v88, -v90, v93, 1.0
	v_fmac_f32_e32 v93, v88, v93
	v_div_scale_f32 v88, vcc, v20, v84, v20
	v_mul_f32_e32 v92, v88, v93
	v_fma_f32 v89, -v90, v92, v88
	v_fmac_f32_e32 v92, v89, v93
	v_fma_f32 v94, -v90, v92, v88
	v_mul_f32_e32 v88, 0xbfb8aa3b, v26
	v_mul_f32_e32 v89, 0xbfb8aa3b, v27
	v_exp_f32_e32 v88, v88
	v_exp_f32_e32 v89, v89
	v_mul_f32_e32 v90, 0xbfb8aa3b, v24
	v_exp_f32_e32 v90, v90
	v_exp_f32_e32 v91, v91
	v_add_f32_e32 v88, 1.0, v88
	v_add_f32_e32 v89, 1.0, v89
	v_div_fmas_f32 v92, v94, v93, v92
	v_div_scale_f32 v95, s[4:5], v89, v89, v27
	v_rcp_f32_e32 v96, v95
	v_div_fixup_f32 v84, v92, v84, v20
	v_add_f32_e32 v92, 1.0, v90
	v_add_f32_e32 v93, 1.0, v91
	v_fma_f32 v90, -v95, v96, 1.0
	v_fmac_f32_e32 v96, v90, v96
	v_div_scale_f32 v90, vcc, v27, v89, v27
	v_mul_f32_e32 v91, v90, v96
	v_fma_f32 v94, -v95, v91, v90
	v_fmac_f32_e32 v91, v94, v96
	v_div_scale_f32 v94, s[4:5], v88, v88, v26
	v_fma_f32 v90, -v95, v91, v90
	v_rcp_f32_e32 v95, v94
	v_div_fmas_f32 v90, v90, v96, v91
	v_div_fixup_f32 v91, v90, v89, v27
	v_fma_f32 v89, -v94, v95, 1.0
	v_fmac_f32_e32 v95, v89, v95
	v_div_scale_f32 v89, vcc, v26, v88, v26
	v_mul_f32_e32 v90, v89, v95
	v_fma_f32 v96, -v94, v90, v89
	v_fmac_f32_e32 v90, v96, v95
	v_fma_f32 v89, -v94, v90, v89
	v_div_scale_f32 v94, s[4:5], v93, v93, v25
	v_rcp_f32_e32 v96, v94
	v_div_fmas_f32 v89, v89, v95, v90
	v_div_fixup_f32 v90, v89, v88, v26
	v_fma_f32 v88, -v94, v96, 1.0
	v_fmac_f32_e32 v96, v88, v96
	v_div_scale_f32 v88, vcc, v25, v93, v25
	v_mul_f32_e32 v89, v88, v96
	v_fma_f32 v95, -v94, v89, v88
	v_fmac_f32_e32 v89, v95, v96
	v_fma_f32 v88, -v94, v89, v88
	v_div_scale_f32 v94, s[4:5], v92, v92, v24
	v_rcp_f32_e32 v98, v94
	v_div_fmas_f32 v88, v88, v96, v89
	v_div_fixup_f32 v89, v88, v93, v25
	v_mul_f32_e32 v96, 0xbfb8aa3b, v28
	v_fma_f32 v88, -v94, v98, 1.0
	v_fmac_f32_e32 v98, v88, v98
	v_div_scale_f32 v88, vcc, v24, v92, v24
	v_mul_f32_e32 v93, v88, v98
	v_fma_f32 v95, -v94, v93, v88
	v_fmac_f32_e32 v93, v95, v98
	v_fma_f32 v88, -v94, v93, v88
	v_mul_f32_e32 v94, 0xbfb8aa3b, v30
	v_mul_f32_e32 v95, 0xbfb8aa3b, v31
	v_exp_f32_e32 v94, v94
	v_exp_f32_e32 v95, v95
	v_exp_f32_e32 v96, v96
	v_div_fmas_f32 v88, v88, v98, v93
	v_div_fixup_f32 v88, v88, v92, v24
	v_add_f32_e32 v94, 1.0, v94
	v_add_f32_e32 v95, 1.0, v95
	v_add_f32_e32 v92, 1.0, v96
	v_add_f32_e32 v93, 1.0, v97
	v_div_scale_f32 v99, s[4:5], v95, v95, v31
	v_rcp_f32_e32 v100, v99
	s_nop 0
	v_fma_f32 v96, -v99, v100, 1.0
	v_fmac_f32_e32 v100, v96, v100
	v_div_scale_f32 v96, vcc, v31, v95, v31
	v_mul_f32_e32 v97, v96, v100
	v_fma_f32 v98, -v99, v97, v96
	v_fmac_f32_e32 v97, v98, v100
	v_div_scale_f32 v98, s[4:5], v94, v94, v30
	v_fma_f32 v96, -v99, v97, v96
	v_rcp_f32_e32 v99, v98
	v_div_fmas_f32 v96, v96, v100, v97
	v_div_fixup_f32 v95, v96, v95, v31
	v_fma_f32 v96, -v98, v99, 1.0
	v_fmac_f32_e32 v99, v96, v99
	v_div_scale_f32 v96, vcc, v30, v94, v30
	v_mul_f32_e32 v97, v96, v99
	v_fma_f32 v100, -v98, v97, v96
	v_fmac_f32_e32 v97, v100, v99
	v_fma_f32 v96, -v98, v97, v96
	v_div_scale_f32 v98, s[4:5], v93, v93, v29
	v_rcp_f32_e32 v100, v98
	v_div_fmas_f32 v96, v96, v99, v97
	v_div_fixup_f32 v94, v96, v94, v30
	v_fma_f32 v96, -v98, v100, 1.0
	v_fmac_f32_e32 v100, v96, v100
	v_div_scale_f32 v96, vcc, v29, v93, v29
	v_mul_f32_e32 v97, v96, v100
	v_fma_f32 v99, -v98, v97, v96
	v_fmac_f32_e32 v97, v99, v100
	v_fma_f32 v96, -v98, v97, v96
	v_div_scale_f32 v98, s[4:5], v92, v92, v28
	v_rcp_f32_e32 v101, v98
	v_div_fmas_f32 v96, v96, v100, v97
	v_div_fixup_f32 v93, v96, v93, v29
	v_mul_f32_e32 v99, 0xbfb8aa3b, v33
	v_fma_f32 v96, -v98, v101, 1.0
	v_fmac_f32_e32 v101, v96, v101
	v_div_scale_f32 v96, vcc, v28, v92, v28
	v_mul_f32_e32 v100, v96, v101
	v_fma_f32 v97, -v98, v100, v96
	v_fmac_f32_e32 v100, v97, v101
	v_fma_f32 v102, -v98, v100, v96
	v_mul_f32_e32 v96, 0xbfb8aa3b, v34
	v_mul_f32_e32 v97, 0xbfb8aa3b, v35
	v_exp_f32_e32 v96, v96
	v_exp_f32_e32 v97, v97
	v_mul_f32_e32 v98, 0xbfb8aa3b, v32
	v_exp_f32_e32 v98, v98
	v_exp_f32_e32 v99, v99
	v_add_f32_e32 v96, 1.0, v96
	v_add_f32_e32 v97, 1.0, v97
	v_div_fmas_f32 v100, v102, v101, v100
	v_div_scale_f32 v103, s[4:5], v97, v97, v35
	v_rcp_f32_e32 v104, v103
	v_div_fixup_f32 v92, v100, v92, v28
	v_add_f32_e32 v100, 1.0, v98
	v_add_f32_e32 v101, 1.0, v99
	v_fma_f32 v98, -v103, v104, 1.0
	v_fmac_f32_e32 v104, v98, v104
	v_div_scale_f32 v98, vcc, v35, v97, v35
	v_mul_f32_e32 v99, v98, v104
	v_fma_f32 v102, -v103, v99, v98
	v_fmac_f32_e32 v99, v102, v104
	v_div_scale_f32 v102, s[4:5], v96, v96, v34
	v_fma_f32 v98, -v103, v99, v98
	v_rcp_f32_e32 v103, v102
	v_div_fmas_f32 v98, v98, v104, v99
	v_div_fixup_f32 v99, v98, v97, v35
	v_fma_f32 v97, -v102, v103, 1.0
	v_fmac_f32_e32 v103, v97, v103
	v_div_scale_f32 v97, vcc, v34, v96, v34
	v_mul_f32_e32 v98, v97, v103
	v_fma_f32 v104, -v102, v98, v97
	v_fmac_f32_e32 v98, v104, v103
	v_fma_f32 v97, -v102, v98, v97
	v_div_scale_f32 v102, s[4:5], v101, v101, v33
	v_rcp_f32_e32 v104, v102
	v_div_fmas_f32 v97, v97, v103, v98
	v_div_fixup_f32 v98, v97, v96, v34
	v_fma_f32 v96, -v102, v104, 1.0
	v_fmac_f32_e32 v104, v96, v104
	v_div_scale_f32 v96, vcc, v33, v101, v33
	v_mul_f32_e32 v97, v96, v104
	v_fma_f32 v103, -v102, v97, v96
	v_fmac_f32_e32 v97, v103, v104
	v_fma_f32 v96, -v102, v97, v96
	v_div_scale_f32 v102, s[4:5], v100, v100, v32
	v_rcp_f32_e32 v106, v102
	v_div_fmas_f32 v96, v96, v104, v97
	v_div_fixup_f32 v97, v96, v101, v33
	v_mul_f32_e32 v104, 0xbfb8aa3b, v36
	v_fma_f32 v96, -v102, v106, 1.0
	v_fmac_f32_e32 v106, v96, v106
	v_div_scale_f32 v96, vcc, v32, v100, v32
	v_mul_f32_e32 v101, v96, v106
	v_fma_f32 v103, -v102, v101, v96
	v_fmac_f32_e32 v101, v103, v106
	v_fma_f32 v96, -v102, v101, v96
	v_mul_f32_e32 v102, 0xbfb8aa3b, v38
	v_mul_f32_e32 v103, 0xbfb8aa3b, v39
	v_exp_f32_e32 v102, v102
	v_exp_f32_e32 v103, v103
	v_exp_f32_e32 v104, v104
	v_div_fmas_f32 v96, v96, v106, v101
	v_div_fixup_f32 v96, v96, v100, v32
	v_add_f32_e32 v102, 1.0, v102
	v_add_f32_e32 v103, 1.0, v103
	v_add_f32_e32 v100, 1.0, v104
	v_add_f32_e32 v101, 1.0, v105
	v_div_scale_f32 v107, s[4:5], v103, v103, v39
	v_rcp_f32_e32 v108, v107
	s_nop 0
	v_fma_f32 v104, -v107, v108, 1.0
	v_fmac_f32_e32 v108, v104, v108
	v_div_scale_f32 v104, vcc, v39, v103, v39
	v_mul_f32_e32 v105, v104, v108
	v_fma_f32 v106, -v107, v105, v104
	v_fmac_f32_e32 v105, v106, v108
	v_div_scale_f32 v106, s[4:5], v102, v102, v38
	v_fma_f32 v104, -v107, v105, v104
	v_rcp_f32_e32 v107, v106
	v_div_fmas_f32 v104, v104, v108, v105
	v_div_fixup_f32 v103, v104, v103, v39
	v_fma_f32 v104, -v106, v107, 1.0
	v_fmac_f32_e32 v107, v104, v107
	v_div_scale_f32 v104, vcc, v38, v102, v38
	v_mul_f32_e32 v105, v104, v107
	v_fma_f32 v108, -v106, v105, v104
	v_fmac_f32_e32 v105, v108, v107
	v_fma_f32 v104, -v106, v105, v104
	v_div_scale_f32 v106, s[4:5], v101, v101, v37
	v_rcp_f32_e32 v108, v106
	v_div_fmas_f32 v104, v104, v107, v105
	v_div_fixup_f32 v102, v104, v102, v38
	v_fma_f32 v104, -v106, v108, 1.0
	v_fmac_f32_e32 v108, v104, v108
	v_div_scale_f32 v104, vcc, v37, v101, v37
	v_mul_f32_e32 v105, v104, v108
	v_fma_f32 v107, -v106, v105, v104
	v_fmac_f32_e32 v105, v107, v108
	v_fma_f32 v104, -v106, v105, v104
	v_div_scale_f32 v106, s[4:5], v100, v100, v36
	v_rcp_f32_e32 v109, v106
	v_div_fmas_f32 v104, v104, v108, v105
	v_div_fixup_f32 v101, v104, v101, v37
	v_mul_f32_e32 v107, 0xbfb8aa3b, v41
	v_fma_f32 v104, -v106, v109, 1.0
	v_fmac_f32_e32 v109, v104, v109
	v_div_scale_f32 v104, vcc, v36, v100, v36
	v_mul_f32_e32 v108, v104, v109
	v_fma_f32 v105, -v106, v108, v104
	v_fmac_f32_e32 v108, v105, v109
	v_fma_f32 v110, -v106, v108, v104
	v_mul_f32_e32 v104, 0xbfb8aa3b, v42
	v_mul_f32_e32 v105, 0xbfb8aa3b, v43
	v_exp_f32_e32 v104, v104
	v_exp_f32_e32 v105, v105
	v_mul_f32_e32 v106, 0xbfb8aa3b, v40
	v_exp_f32_e32 v106, v106
	v_exp_f32_e32 v107, v107
	v_add_f32_e32 v104, 1.0, v104
	v_add_f32_e32 v105, 1.0, v105
	v_div_fmas_f32 v108, v110, v109, v108
	v_div_scale_f32 v111, s[4:5], v105, v105, v43
	v_rcp_f32_e32 v112, v111
	v_div_fixup_f32 v100, v108, v100, v36
	v_add_f32_e32 v108, 1.0, v106
	v_add_f32_e32 v109, 1.0, v107
	v_fma_f32 v106, -v111, v112, 1.0
	v_fmac_f32_e32 v112, v106, v112
	v_div_scale_f32 v106, vcc, v43, v105, v43
	v_mul_f32_e32 v107, v106, v112
	v_fma_f32 v110, -v111, v107, v106
	v_fmac_f32_e32 v107, v110, v112
	v_div_scale_f32 v110, s[4:5], v104, v104, v42
	v_fma_f32 v106, -v111, v107, v106
	v_rcp_f32_e32 v111, v110
	v_div_fmas_f32 v106, v106, v112, v107
	v_div_fixup_f32 v107, v106, v105, v43
	v_fma_f32 v105, -v110, v111, 1.0
	v_fmac_f32_e32 v111, v105, v111
	v_div_scale_f32 v105, vcc, v42, v104, v42
	v_mul_f32_e32 v106, v105, v111
	v_fma_f32 v112, -v110, v106, v105
	v_fmac_f32_e32 v106, v112, v111
	v_fma_f32 v105, -v110, v106, v105
	v_div_scale_f32 v110, s[4:5], v109, v109, v41
	v_rcp_f32_e32 v112, v110
	v_div_fmas_f32 v105, v105, v111, v106
	v_div_fixup_f32 v106, v105, v104, v42
	v_fma_f32 v104, -v110, v112, 1.0
	v_fmac_f32_e32 v112, v104, v112
	v_div_scale_f32 v104, vcc, v41, v109, v41
	v_mul_f32_e32 v105, v104, v112
	v_fma_f32 v111, -v110, v105, v104
	v_fmac_f32_e32 v105, v111, v112
	v_fma_f32 v104, -v110, v105, v104
	v_div_scale_f32 v110, s[4:5], v108, v108, v40
	v_rcp_f32_e32 v114, v110
	v_div_fmas_f32 v104, v104, v112, v105
	v_div_fixup_f32 v105, v104, v109, v41
	v_mul_f32_e32 v112, 0xbfb8aa3b, v44
	v_fma_f32 v104, -v110, v114, 1.0
	v_fmac_f32_e32 v114, v104, v114
	v_div_scale_f32 v104, vcc, v40, v108, v40
	v_mul_f32_e32 v109, v104, v114
	v_fma_f32 v111, -v110, v109, v104
	v_fmac_f32_e32 v109, v111, v114
	v_fma_f32 v104, -v110, v109, v104
	v_mul_f32_e32 v110, 0xbfb8aa3b, v46
	v_mul_f32_e32 v111, 0xbfb8aa3b, v47
	v_exp_f32_e32 v110, v110
	v_exp_f32_e32 v111, v111
	v_exp_f32_e32 v112, v112
	v_div_fmas_f32 v104, v104, v114, v109
	v_div_fixup_f32 v104, v104, v108, v40
	v_add_f32_e32 v110, 1.0, v110
	v_add_f32_e32 v111, 1.0, v111
	v_add_f32_e32 v108, 1.0, v112
	v_add_f32_e32 v109, 1.0, v113
	v_div_scale_f32 v115, s[4:5], v111, v111, v47
	v_rcp_f32_e32 v116, v115
	s_nop 0
	v_fma_f32 v112, -v115, v116, 1.0
	v_fmac_f32_e32 v116, v112, v116
	v_div_scale_f32 v112, vcc, v47, v111, v47
	v_mul_f32_e32 v113, v112, v116
	v_fma_f32 v114, -v115, v113, v112
	v_fmac_f32_e32 v113, v114, v116
	v_div_scale_f32 v114, s[4:5], v110, v110, v46
	v_fma_f32 v112, -v115, v113, v112
	v_rcp_f32_e32 v115, v114
	v_div_fmas_f32 v112, v112, v116, v113
	v_div_fixup_f32 v111, v112, v111, v47
	v_fma_f32 v112, -v114, v115, 1.0
	v_fmac_f32_e32 v115, v112, v115
	v_div_scale_f32 v112, vcc, v46, v110, v46
	v_mul_f32_e32 v113, v112, v115
	v_fma_f32 v116, -v114, v113, v112
	v_fmac_f32_e32 v113, v116, v115
	v_fma_f32 v112, -v114, v113, v112
	v_div_scale_f32 v114, s[4:5], v109, v109, v45
	v_rcp_f32_e32 v116, v114
	v_div_fmas_f32 v112, v112, v115, v113
	v_div_fixup_f32 v110, v112, v110, v46
	v_fma_f32 v112, -v114, v116, 1.0
	v_fmac_f32_e32 v116, v112, v116
	v_div_scale_f32 v112, vcc, v45, v109, v45
	v_mul_f32_e32 v113, v112, v116
	v_fma_f32 v115, -v114, v113, v112
	v_fmac_f32_e32 v113, v115, v116
	v_fma_f32 v112, -v114, v113, v112
	v_div_scale_f32 v114, s[4:5], v108, v108, v44
	v_rcp_f32_e32 v117, v114
	v_div_fmas_f32 v112, v112, v116, v113
	v_div_fixup_f32 v109, v112, v109, v45
	v_mul_f32_e32 v115, 0xbfb8aa3b, v49
	v_fma_f32 v112, -v114, v117, 1.0
	v_fmac_f32_e32 v117, v112, v117
	v_div_scale_f32 v112, vcc, v44, v108, v44
	v_mul_f32_e32 v116, v112, v117
	v_fma_f32 v113, -v114, v116, v112
	v_fmac_f32_e32 v116, v113, v117
	v_fma_f32 v118, -v114, v116, v112
	v_mul_f32_e32 v112, 0xbfb8aa3b, v50
	v_mul_f32_e32 v113, 0xbfb8aa3b, v51
	v_exp_f32_e32 v112, v112
	v_exp_f32_e32 v113, v113
	v_mul_f32_e32 v114, 0xbfb8aa3b, v48
	v_exp_f32_e32 v114, v114
	v_exp_f32_e32 v115, v115
	v_add_f32_e32 v112, 1.0, v112
	v_add_f32_e32 v113, 1.0, v113
	v_div_fmas_f32 v116, v118, v117, v116
	v_div_scale_f32 v119, s[4:5], v113, v113, v51
	v_rcp_f32_e32 v120, v119
	v_div_fixup_f32 v108, v116, v108, v44
	v_add_f32_e32 v116, 1.0, v114
	v_add_f32_e32 v117, 1.0, v115
	v_fma_f32 v114, -v119, v120, 1.0
	v_fmac_f32_e32 v120, v114, v120
	v_div_scale_f32 v114, vcc, v51, v113, v51
	v_mul_f32_e32 v115, v114, v120
	v_fma_f32 v118, -v119, v115, v114
	v_fmac_f32_e32 v115, v118, v120
	v_div_scale_f32 v118, s[4:5], v112, v112, v50
	v_fma_f32 v114, -v119, v115, v114
	v_rcp_f32_e32 v119, v118
	v_div_fmas_f32 v114, v114, v120, v115
	v_div_fixup_f32 v115, v114, v113, v51
	v_fma_f32 v113, -v118, v119, 1.0
	v_fmac_f32_e32 v119, v113, v119
	v_div_scale_f32 v113, vcc, v50, v112, v50
	v_mul_f32_e32 v114, v113, v119
	v_fma_f32 v120, -v118, v114, v113
	v_fmac_f32_e32 v114, v120, v119
	v_fma_f32 v113, -v118, v114, v113
	v_div_scale_f32 v118, s[4:5], v117, v117, v49
	v_rcp_f32_e32 v120, v118
	v_div_fmas_f32 v113, v113, v119, v114
	v_div_fixup_f32 v114, v113, v112, v50
	v_fma_f32 v112, -v118, v120, 1.0
	v_fmac_f32_e32 v120, v112, v120
	v_div_scale_f32 v112, vcc, v49, v117, v49
	v_mul_f32_e32 v113, v112, v120
	v_fma_f32 v119, -v118, v113, v112
	v_fmac_f32_e32 v113, v119, v120
	v_fma_f32 v112, -v118, v113, v112
	v_div_scale_f32 v118, s[4:5], v116, v116, v48
	v_rcp_f32_e32 v122, v118
	v_div_fmas_f32 v112, v112, v120, v113
	v_div_fixup_f32 v113, v112, v117, v49
	v_mul_f32_e32 v120, 0xbfb8aa3b, v52
	v_fma_f32 v112, -v118, v122, 1.0
	v_fmac_f32_e32 v122, v112, v122
	v_div_scale_f32 v112, vcc, v48, v116, v48
	v_mul_f32_e32 v117, v112, v122
	v_fma_f32 v119, -v118, v117, v112
	v_fmac_f32_e32 v117, v119, v122
	v_fma_f32 v112, -v118, v117, v112
	v_mul_f32_e32 v118, 0xbfb8aa3b, v54
	v_mul_f32_e32 v119, 0xbfb8aa3b, v55
	v_exp_f32_e32 v118, v118
	v_exp_f32_e32 v119, v119
	v_exp_f32_e32 v120, v120
	v_div_fmas_f32 v112, v112, v122, v117
	v_div_fixup_f32 v112, v112, v116, v48
	v_add_f32_e32 v118, 1.0, v118
	v_add_f32_e32 v119, 1.0, v119
	v_add_f32_e32 v116, 1.0, v120
	v_add_f32_e32 v117, 1.0, v121
	v_div_scale_f32 v123, s[4:5], v119, v119, v55
	v_rcp_f32_e32 v124, v123
	s_nop 0
	v_fma_f32 v120, -v123, v124, 1.0
	v_fmac_f32_e32 v124, v120, v124
	v_div_scale_f32 v120, vcc, v55, v119, v55
	v_mul_f32_e32 v121, v120, v124
	v_fma_f32 v122, -v123, v121, v120
	v_fmac_f32_e32 v121, v122, v124
	v_div_scale_f32 v122, s[4:5], v118, v118, v54
	v_fma_f32 v120, -v123, v121, v120
	v_rcp_f32_e32 v123, v122
	v_div_fmas_f32 v120, v120, v124, v121
	v_div_fixup_f32 v119, v120, v119, v55
	v_fma_f32 v120, -v122, v123, 1.0
	v_fmac_f32_e32 v123, v120, v123
	v_div_scale_f32 v120, vcc, v54, v118, v54
	v_mul_f32_e32 v121, v120, v123
	v_fma_f32 v124, -v122, v121, v120
	v_fmac_f32_e32 v121, v124, v123
	v_fma_f32 v120, -v122, v121, v120
	v_div_scale_f32 v122, s[4:5], v117, v117, v53
	v_rcp_f32_e32 v124, v122
	v_div_fmas_f32 v120, v120, v123, v121
	v_div_fixup_f32 v118, v120, v118, v54
	v_fma_f32 v120, -v122, v124, 1.0
	v_fmac_f32_e32 v124, v120, v124
	v_div_scale_f32 v120, vcc, v53, v117, v53
	v_mul_f32_e32 v121, v120, v124
	v_fma_f32 v123, -v122, v121, v120
	v_fmac_f32_e32 v121, v123, v124
	v_fma_f32 v120, -v122, v121, v120
	v_div_scale_f32 v122, s[4:5], v116, v116, v52
	v_rcp_f32_e32 v125, v122
	v_div_fmas_f32 v120, v120, v124, v121
	v_div_fixup_f32 v117, v120, v117, v53
	v_mul_f32_e32 v123, 0xbfb8aa3b, v57
	v_fma_f32 v120, -v122, v125, 1.0
	v_fmac_f32_e32 v125, v120, v125
	v_div_scale_f32 v120, vcc, v52, v116, v52
	v_mul_f32_e32 v124, v120, v125
	v_fma_f32 v121, -v122, v124, v120
	v_fmac_f32_e32 v124, v121, v125
	v_fma_f32 v126, -v122, v124, v120
	v_mul_f32_e32 v120, 0xbfb8aa3b, v58
	v_mul_f32_e32 v121, 0xbfb8aa3b, v59
	v_exp_f32_e32 v120, v120
	v_exp_f32_e32 v121, v121
	v_mul_f32_e32 v122, 0xbfb8aa3b, v56
	v_exp_f32_e32 v122, v122
	v_exp_f32_e32 v123, v123
	v_add_f32_e32 v120, 1.0, v120
	v_add_f32_e32 v121, 1.0, v121
	v_div_fmas_f32 v124, v126, v125, v124
	v_div_scale_f32 v127, s[4:5], v121, v121, v59
	v_rcp_f32_e32 v142, v127
	v_div_fixup_f32 v116, v124, v116, v52
	v_add_f32_e32 v124, 1.0, v122
	v_add_f32_e32 v125, 1.0, v123
	v_fma_f32 v122, -v127, v142, 1.0
	v_fmac_f32_e32 v142, v122, v142
	v_div_scale_f32 v122, vcc, v59, v121, v59
	v_mul_f32_e32 v123, v122, v142
	v_fma_f32 v126, -v127, v123, v122
	v_fmac_f32_e32 v123, v126, v142
	v_div_scale_f32 v126, s[4:5], v120, v120, v58
	v_fma_f32 v122, -v127, v123, v122
	v_rcp_f32_e32 v127, v126
	v_div_fmas_f32 v122, v122, v142, v123
	v_div_fixup_f32 v123, v122, v121, v59
	v_fma_f32 v121, -v126, v127, 1.0
	v_fmac_f32_e32 v127, v121, v127
	v_div_scale_f32 v121, vcc, v58, v120, v58
	v_mul_f32_e32 v122, v121, v127
	v_fma_f32 v142, -v126, v122, v121
	v_fmac_f32_e32 v122, v142, v127
	v_fma_f32 v121, -v126, v122, v121
	v_div_scale_f32 v126, s[4:5], v125, v125, v57
	v_rcp_f32_e32 v142, v126
	v_div_fmas_f32 v121, v121, v127, v122
	v_div_fixup_f32 v122, v121, v120, v58
	v_fma_f32 v120, -v126, v142, 1.0
	v_fmac_f32_e32 v142, v120, v142
	v_div_scale_f32 v120, vcc, v57, v125, v57
	v_mul_f32_e32 v121, v120, v142
	v_fma_f32 v127, -v126, v121, v120
	v_fmac_f32_e32 v121, v127, v142
	v_fma_f32 v120, -v126, v121, v120
	v_div_scale_f32 v126, s[4:5], v124, v124, v56
	v_rcp_f32_e32 v202, v126
	v_div_fmas_f32 v120, v120, v142, v121
	v_div_fixup_f32 v121, v120, v125, v57
	v_mul_f32_e32 v142, 0xbfb8aa3b, v60
	v_fma_f32 v120, -v126, v202, 1.0
	v_fmac_f32_e32 v202, v120, v202
	v_div_scale_f32 v120, vcc, v56, v124, v56
	v_mul_f32_e32 v125, v120, v202
	v_fma_f32 v127, -v126, v125, v120
	v_fmac_f32_e32 v125, v127, v202
	v_fma_f32 v120, -v126, v125, v120
	v_mul_f32_e32 v126, 0xbfb8aa3b, v62
	v_mul_f32_e32 v127, 0xbfb8aa3b, v63
	v_exp_f32_e32 v126, v126
	v_exp_f32_e32 v127, v127
	v_exp_f32_e32 v200, v142
	v_mul_f32_e32 v142, 0xbfb8aa3b, v61
	v_exp_f32_e32 v201, v142
	v_add_f32_e32 v126, 1.0, v126
	v_add_f32_e32 v127, 1.0, v127
	v_div_fmas_f32 v120, v120, v202, v125
	v_div_scale_f32 v142, s[4:5], v127, v127, v63
	v_rcp_f32_e32 v203, v142
	v_div_fixup_f32 v120, v120, v124, v56
	v_add_f32_e32 v124, 1.0, v200
	v_add_f32_e32 v125, 1.0, v201
	v_fma_f32 v200, -v142, v203, 1.0
	v_fmac_f32_e32 v203, v200, v203
	v_div_scale_f32 v200, vcc, v63, v127, v63
	v_mul_f32_e32 v201, v200, v203
	v_fma_f32 v202, -v142, v201, v200
	v_fmac_f32_e32 v201, v202, v203
	v_fma_f32 v142, -v142, v201, v200
	v_div_scale_f32 v200, s[4:5], v126, v126, v62
	v_rcp_f32_e32 v202, v200
	v_div_fmas_f32 v142, v142, v203, v201
	v_div_fixup_f32 v127, v142, v127, v63
	v_fma_f32 v142, -v200, v202, 1.0
	v_fmac_f32_e32 v202, v142, v202
	v_div_scale_f32 v142, vcc, v62, v126, v62
	v_mul_f32_e32 v201, v142, v202
	v_fma_f32 v203, -v200, v201, v142
	v_fmac_f32_e32 v201, v203, v202
	v_fma_f32 v142, -v200, v201, v142
	v_div_scale_f32 v200, s[4:5], v125, v125, v61
	v_rcp_f32_e32 v203, v200
	v_div_fmas_f32 v142, v142, v202, v201
	v_div_fixup_f32 v126, v142, v126, v62
	v_fma_f32 v142, -v200, v203, 1.0
	v_fmac_f32_e32 v203, v142, v203
	v_div_scale_f32 v142, vcc, v61, v125, v61
	v_mul_f32_e32 v201, v142, v203
	v_fma_f32 v202, -v200, v201, v142
	v_fmac_f32_e32 v201, v202, v203
	v_fma_f32 v142, -v200, v201, v142
	v_div_scale_f32 v200, s[4:5], v124, v124, v60
	v_rcp_f32_e32 v202, v200
	v_div_fmas_f32 v142, v142, v203, v201
	v_div_fixup_f32 v125, v142, v125, v61
	s_lshl_b64 s[4:5], s[66:67], 19
	v_fma_f32 v142, -v200, v202, 1.0
	v_fmac_f32_e32 v202, v142, v202
	v_div_scale_f32 v142, vcc, v60, v124, v60
	s_add_u32 s4, s36, s4
	v_mul_f32_e32 v201, v142, v202
	s_addc_u32 s5, s37, s5
	s_lshl_b32 s34, s0, 7
	v_fma_f32 v203, -v200, v201, v142
	s_lshl_b64 s[0:1], s[34:35], 1
	v_fmac_f32_e32 v201, v203, v202
	s_add_u32 s0, s4, s0
	v_fma_f32 v142, -v200, v201, v142
	s_addc_u32 s1, s5, s1
	v_div_fmas_f32 v142, v142, v202, v201
	s_add_u32 s4, s0, 0xffffd800
	v_div_fixup_f32 v124, v142, v124, v60
	s_addc_u32 s5, s1, -1

.LBB0_178:
	s_andn2_b64 vcc, exec, s[0:1]
	s_mov_b64 s[0:1], 0x1000
	s_cbranch_vccnz .LBB0_189
	s_cmp_lg_u32 s77, 0
	s_cbranch_scc0 .LBB0_195
	s_cmp_lg_u32 s77, 1
	s_cselect_b64 s[72:73], -1, 0
	s_lshl_b32 s0, s76, 9
	s_add_u32 s4, s82, s0
	s_addc_u32 s5, s83, 0
	s_cmp_eq_u32 s77, 2
	s_cselect_b64 s[70:71], -1, 0
	s_and_b64 s[0:1], s[70:71], exec
	s_cselect_b32 s1, s57, s59
	s_cselect_b32 s0, s56, s58
	s_cmp_eq_u32 s77, 1
	s_cselect_b32 s0, s4, s0
	s_cselect_b32 s1, s5, s1
	global_load_dword v98, v190, s[0:1]
	global_load_dword v116, v190, s[0:1] offset:320
	global_load_dword v120, v190, s[0:1] offset:384
	global_load_dword v102, v190, s[0:1] offset:64
	global_load_dword v106, v190, s[0:1] offset:128
	v_and_b32_e32 v65, 64, v199
	global_load_dword v110, v190, s[0:1] offset:192
	v_xor_b32_e32 v64, 1, v199
	v_add_u32_e32 v65, 64, v65
	global_load_dword v112, v190, s[0:1] offset:256
	global_load_dword v124, v190, s[0:1] offset:448
	v_cmp_lt_i32_e32 vcc, v64, v65
	v_mul_f32_e32 v66, v4, v4
	v_mul_f32_e32 v67, v5, v5
	v_mul_f32_e32 v70, v36, v36
	v_mul_f32_e32 v71, v37, v37
	v_cndmask_b32_e32 v64, v199, v64, vcc
	v_fma_f32 v66, v0, v0, v66
	v_fma_f32 v67, v1, v1, v67
	v_lshlrev_b32_e32 v99, 2, v64
	v_xor_b32_e32 v64, 2, v199
	v_fma_f32 v66, v8, v8, v66
	v_fma_f32 v67, v9, v9, v67
	v_cmp_lt_i32_e32 vcc, v64, v65
	v_fma_f32 v66, v12, v12, v66
	v_fma_f32 v67, v13, v13, v67
	v_fma_f32 v70, v32, v32, v70
	v_fma_f32 v71, v33, v33, v71
	v_cndmask_b32_e32 v64, v199, v64, vcc
	v_fma_f32 v66, v16, v16, v66
	v_fma_f32 v67, v17, v17, v67
	v_lshlrev_b32_e32 v103, 2, v64
	v_xor_b32_e32 v64, 4, v199
	v_fma_f32 v66, v20, v20, v66
	v_fma_f32 v67, v21, v21, v67
	v_cmp_lt_i32_e32 vcc, v64, v65
	v_fma_f32 v66, v24, v24, v66
	v_fma_f32 v67, v25, v25, v67
	v_fma_f32 v70, v40, v40, v70
	v_fma_f32 v71, v41, v41, v71
	v_cndmask_b32_e32 v64, v199, v64, vcc
	v_fma_f32 v66, v28, v28, v66
	v_fma_f32 v67, v29, v29, v67
	v_lshlrev_b32_e32 v107, 2, v64
	v_xor_b32_e32 v64, 8, v199
	ds_bpermute_b32 v72, v99, v66
	ds_bpermute_b32 v73, v99, v67
	v_cmp_lt_i32_e32 vcc, v64, v65
	v_fma_f32 v70, v44, v44, v70
	v_fma_f32 v71, v45, v45, v71
	v_mul_f32_e32 v68, v38, v38
	v_mul_f32_e32 v69, v39, v39
	v_cndmask_b32_e32 v64, v199, v64, vcc
	v_lshlrev_b32_e32 v111, 2, v64
	v_mul_f32_e32 v64, v6, v6
	v_mul_f32_e32 v65, v7, v7
	s_waitcnt lgkmcnt(0)
	v_add_f32_e32 v66, v66, v72
	v_add_f32_e32 v67, v67, v73
	v_fma_f32 v64, v2, v2, v64
	v_fma_f32 v65, v3, v3, v65
	ds_bpermute_b32 v72, v103, v66
	v_fma_f32 v64, v10, v10, v64
	v_fma_f32 v65, v11, v11, v65
	ds_bpermute_b32 v73, v103, v67
	v_fma_f32 v64, v14, v14, v64
	v_fma_f32 v65, v15, v15, v65
	v_fma_f32 v70, v48, v48, v70
	v_fma_f32 v71, v49, v49, v71
	v_fma_f32 v64, v18, v18, v64
	v_fma_f32 v65, v19, v19, v65
	v_fma_f32 v70, v52, v52, v70
	v_fma_f32 v71, v53, v53, v71
	v_fma_f32 v64, v22, v22, v64
	v_fma_f32 v65, v23, v23, v65
	s_waitcnt lgkmcnt(0)
	v_add_f32_e32 v66, v66, v72
	v_add_f32_e32 v67, v67, v73
	v_fma_f32 v64, v26, v26, v64
	v_fma_f32 v65, v27, v27, v65
	v_fma_f32 v80, v56, v56, v70
	v_fma_f32 v81, v57, v57, v71
	v_fma_f32 v64, v30, v30, v64
	v_fma_f32 v65, v31, v31, v65
	ds_bpermute_b32 v74, v99, v64
	ds_bpermute_b32 v75, v99, v65
	ds_bpermute_b32 v72, v107, v66
	ds_bpermute_b32 v73, v107, v67
	v_fma_f32 v84, v60, v60, v80
	v_fma_f32 v85, v61, v61, v81
	v_fma_f32 v68, v34, v34, v68
	v_fma_f32 v69, v35, v35, v69
	ds_bpermute_b32 v86, v99, v84
	ds_bpermute_b32 v87, v99, v85
	v_fma_f32 v68, v42, v42, v68
	v_fma_f32 v69, v43, v43, v69
	s_waitcnt lgkmcnt(0)
	v_add_f32_e32 v64, v64, v74
	v_add_f32_e32 v65, v65, v75
	v_fma_f32 v68, v46, v46, v68
	v_fma_f32 v69, v47, v47, v69
	v_add_f32_e32 v66, v66, v72
	v_add_f32_e32 v67, v67, v73
	v_fma_f32 v68, v50, v50, v68
	v_fma_f32 v69, v51, v51, v69
	ds_bpermute_b32 v72, v103, v64
	v_fma_f32 v68, v54, v54, v68
	v_fma_f32 v69, v55, v55, v69
	ds_bpermute_b32 v73, v103, v65
	v_fma_f32 v96, v58, v58, v68
	v_fma_f32 v97, v59, v59, v69
	ds_bpermute_b32 v68, v111, v66
	ds_bpermute_b32 v69, v111, v67
	v_add_f32_e32 v90, v84, v86
	v_add_f32_e32 v91, v85, v87
	ds_bpermute_b32 v100, v103, v90
	ds_bpermute_b32 v101, v103, v91
	s_waitcnt lgkmcnt(0)
	v_add_f32_e32 v64, v64, v72
	v_add_f32_e32 v65, v65, v73
	v_add_f32_e32 v66, v66, v68
	v_add_f32_e32 v67, v67, v69
	ds_bpermute_b32 v68, v107, v64
	ds_bpermute_b32 v69, v107, v65
	v_add_f32_e32 v100, v90, v100
	v_add_f32_e32 v101, v91, v101
	ds_bpermute_b32 v108, v107, v100
	ds_bpermute_b32 v109, v107, v101
	v_mov_b64_e32 v[104:105], s[46:47]
	s_waitcnt lgkmcnt(0)
	v_add_f32_e32 v64, v64, v68
	v_add_f32_e32 v65, v65, v69
	ds_bpermute_b32 v68, v111, v64
	ds_bpermute_b32 v69, v111, v65
	v_add_f32_e32 v100, v100, v108
	v_add_f32_e32 v101, v101, v109
	ds_bpermute_b32 v108, v111, v100
	ds_bpermute_b32 v109, v111, v101
	v_fma_f32 v66, v66, s38, v104
	v_fma_f32 v67, v67, s38, v104
	s_waitcnt lgkmcnt(0)
	v_add_f32_e32 v64, v64, v68
	v_add_f32_e32 v65, v65, v69
	v_mul_f32_e32 v70, 0x4b800000, v66
	v_cmp_gt_f32_e32 vcc, s47, v66
	v_fma_f32 v64, v64, s38, v104
	v_fma_f32 v65, v65, s38, v104
	v_fma_f32 v96, v62, v62, v96
	v_fma_f32 v97, v63, v63, v97
	v_cndmask_b32_e32 v66, v66, v70, vcc
	v_mul_f32_e32 v70, 0x4b800000, v67
	v_cmp_gt_f32_e64 s[0:1], s47, v67
	v_mul_f32_e32 v68, 0x4b800000, v64
	v_cmp_gt_f32_e64 s[4:5], s47, v64
	v_add_f32_e32 v100, v100, v108
	v_add_f32_e32 v101, v101, v109
	ds_bpermute_b32 v108, v99, v96
	ds_bpermute_b32 v109, v99, v97
	v_cndmask_b32_e64 v67, v67, v70, s[0:1]
	v_cndmask_b32_e64 v64, v64, v68, s[4:5]
	v_mul_f32_e32 v68, 0x4b800000, v65
	v_cmp_gt_f32_e64 s[6:7], s47, v65
	v_rsq_f32_e32 v66, v66
	v_rsq_f32_e32 v67, v67
	v_cndmask_b32_e64 v65, v65, v68, s[6:7]
	v_rsq_f32_e32 v64, v64
	v_rsq_f32_e32 v65, v65
	s_waitcnt lgkmcnt(0)
	v_add_f32_e32 v96, v96, v108
	v_add_f32_e32 v97, v97, v109
	v_mul_f32_e32 v68, s52, v66
	v_mul_f32_e32 v69, s52, v67
	ds_bpermute_b32 v108, v103, v96
	ds_bpermute_b32 v109, v103, v97
	v_cndmask_b32_e64 v93, v67, v69, s[0:1]
	v_cndmask_b32_e32 v92, v66, v68, vcc
	v_mul_f32_e32 v66, s52, v64
	v_mul_f32_e32 v67, s52, v65
	v_fma_f32 v100, v100, s38, v104
	v_fma_f32 v101, v101, s38, v104
	v_cndmask_b32_e64 v95, v65, v67, s[6:7]
	v_cndmask_b32_e64 v94, v64, v66, s[4:5]
	s_waitcnt vmcnt(0)
	v_mul_f32_e32 v64, v94, v98
	v_mul_f32_e32 v65, v95, v98
	v_mul_f32_e32 v68, v92, v98
	v_mul_f32_e32 v69, v93, v98
	v_mul_f32_e32 v99, 0x4b800000, v100
	v_cmp_gt_f32_e32 vcc, s47, v100
	v_cmp_gt_f32_e64 s[0:1], s47, v101
	s_waitcnt lgkmcnt(0)
	v_add_f32_e32 v96, v96, v108
	v_add_f32_e32 v97, v97, v109
	v_cndmask_b32_e32 v99, v100, v99, vcc
	v_rsq_f32_e32 v100, v99
	v_mul_f32_e32 v99, 0x4b800000, v101
	v_cndmask_b32_e64 v99, v101, v99, s[0:1]
	ds_bpermute_b32 v108, v107, v96
	ds_bpermute_b32 v109, v107, v97
	v_rsq_f32_e32 v101, v99
	v_mul_f32_e32 v88, v94, v116
	v_mul_f32_e32 v89, v95, v116
	v_mul_f32_e32 v114, v92, v120
	v_mul_f32_e32 v115, v93, v120
	v_mul_f32_e32 v86, v22, v88
	v_mul_f32_e32 v87, v23, v89
	v_mul_f32_e32 v88, v94, v120
	v_mul_f32_e32 v89, v95, v120
	s_waitcnt lgkmcnt(0)
	v_add_f32_e32 v108, v96, v108
	v_add_f32_e32 v109, v97, v109
	v_mul_f32_e32 v90, v26, v88
	v_mul_f32_e32 v91, v27, v89
	v_mul_f32_e32 v88, v24, v114
	v_mul_f32_e32 v89, v25, v115
	v_mul_f32_e32 v114, s52, v100
	v_mul_f32_e32 v115, s52, v101
	v_mul_f32_e32 v66, v2, v64
	v_mul_f32_e32 v67, v3, v65
	v_cndmask_b32_e64 v127, v101, v115, s[0:1]
	v_cndmask_b32_e32 v126, v100, v114, vcc
	ds_bpermute_b32 v114, v111, v108
	ds_bpermute_b32 v115, v111, v109
	v_mul_f32_e32 v100, v126, v98
	v_mul_f32_e32 v101, v127, v98
	v_mul_f32_e32 v64, v0, v68
	v_mul_f32_e32 v65, v1, v69
	v_mul_f32_e32 v68, v94, v102
	v_mul_f32_e32 v69, v95, v102
	v_mul_f32_e32 v72, v92, v102
	v_mul_f32_e32 v73, v93, v102
	s_waitcnt lgkmcnt(0)
	v_add_f32_e32 v108, v108, v114
	v_add_f32_e32 v109, v109, v115
	v_mul_f32_e32 v118, v126, v106
	v_mul_f32_e32 v119, v127, v106
	v_fma_f32 v105, v109, s38, v104
	v_fma_f32 v104, v108, s38, v104
	v_mul_f32_e32 v70, v6, v68
	v_mul_f32_e32 v71, v7, v69
	v_mul_f32_e32 v99, 0x4b800000, v104
	v_cmp_gt_f32_e32 vcc, s47, v104
	v_cmp_gt_f32_e64 s[0:1], s47, v105
	v_mul_f32_e32 v68, v4, v72
	v_mul_f32_e32 v69, v5, v73
	v_cndmask_b32_e32 v99, v104, v99, vcc
	v_rsq_f32_e32 v114, v99
	v_mul_f32_e32 v99, 0x4b800000, v105
	v_cndmask_b32_e64 v99, v105, v99, s[0:1]
	v_rsq_f32_e32 v115, v99
	v_mul_f32_e32 v72, v94, v106
	v_mul_f32_e32 v73, v95, v106
	v_mul_f32_e32 v76, v92, v106
	v_mul_f32_e32 v77, v93, v106
	v_mul_f32_e32 v104, v40, v118
	v_mul_f32_e32 v105, v41, v119
	v_mul_f32_e32 v118, s52, v114
	v_mul_f32_e32 v119, s52, v115
	v_mul_f32_e32 v74, v10, v72
	v_mul_f32_e32 v75, v11, v73
	v_mul_f32_e32 v72, v8, v76
	v_mul_f32_e32 v73, v9, v77
	v_mul_f32_e32 v76, v94, v110
	v_mul_f32_e32 v77, v95, v110
	v_mul_f32_e32 v82, v92, v110
	v_mul_f32_e32 v83, v93, v110
	v_cndmask_b32_e64 v201, v115, v119, s[0:1]
	v_cndmask_b32_e32 v200, v114, v118, vcc
	v_mul_f32_e32 v78, v14, v76
	v_mul_f32_e32 v79, v15, v77
	v_mul_f32_e32 v76, v12, v82
	v_mul_f32_e32 v77, v13, v83
	v_mul_f32_e32 v82, v94, v112
	v_mul_f32_e32 v83, v95, v112
	v_mul_f32_e32 v80, v92, v112
	v_mul_f32_e32 v81, v93, v112
	v_mul_f32_e32 v84, v92, v116
	v_mul_f32_e32 v85, v93, v116
	v_mul_f32_e32 v94, v94, v124
	v_mul_f32_e32 v95, v95, v124
	v_mul_f32_e32 v92, v92, v124
	v_mul_f32_e32 v93, v93, v124
	v_mul_f32_e32 v96, v32, v100
	v_mul_f32_e32 v97, v33, v101
	v_mul_f32_e32 v100, v126, v102
	v_mul_f32_e32 v101, v127, v102
	v_mul_f32_e32 v108, v126, v110
	v_mul_f32_e32 v109, v127, v110
	v_mul_f32_e32 v99, v98, v201
	v_mul_f32_e32 v98, v98, v200
	v_mul_f32_e32 v103, v102, v201
	v_mul_f32_e32 v102, v102, v200
	v_mul_f32_e32 v107, v106, v201
	v_mul_f32_e32 v106, v106, v200
	v_mul_f32_e32 v111, v110, v201
	v_mul_f32_e32 v110, v110, v200
	v_mul_f32_e32 v114, v200, v112
	v_mul_f32_e32 v115, v201, v112
	v_mul_f32_e32 v113, v127, v112
	v_mul_f32_e32 v112, v126, v112
	v_mul_f32_e32 v118, v200, v116
	v_mul_f32_e32 v119, v201, v116
	v_mul_f32_e32 v117, v127, v116
	v_mul_f32_e32 v116, v126, v116
	v_mul_f32_e32 v122, v200, v120
	v_mul_f32_e32 v123, v201, v120
	v_mul_f32_e32 v121, v127, v120
	v_mul_f32_e32 v120, v126, v120
	v_mul_f32_e32 v200, v200, v124
	v_mul_f32_e32 v201, v201, v124
	v_mul_f32_e32 v125, v127, v124
	v_mul_f32_e32 v124, v126, v124
	s_cmp_lg_u32 s77, 2
	v_mul_f32_e32 v82, v18, v82
	v_mul_f32_e32 v83, v19, v83
	v_mul_f32_e32 v80, v16, v80
	v_mul_f32_e32 v81, v17, v81
	v_mul_f32_e32 v84, v20, v84
	v_mul_f32_e32 v85, v21, v85
	v_mul_f32_e32 v94, v30, v94
	v_mul_f32_e32 v95, v31, v95
	v_mul_f32_e32 v92, v28, v92
	v_mul_f32_e32 v93, v29, v93
	v_mul_f32_e32 v100, v36, v100
	v_mul_f32_e32 v101, v37, v101
	v_mul_f32_e32 v108, v44, v108
	v_mul_f32_e32 v109, v45, v109
	v_mul_f32_e32 v98, v34, v98
	v_mul_f32_e32 v99, v35, v99
	v_mul_f32_e32 v102, v38, v102
	v_mul_f32_e32 v103, v39, v103
	v_mul_f32_e32 v106, v42, v106
	v_mul_f32_e32 v107, v43, v107
	v_mul_f32_e32 v110, v46, v110
	v_mul_f32_e32 v111, v47, v111
	v_mul_f32_e32 v114, v50, v114
	v_mul_f32_e32 v115, v51, v115
	v_mul_f32_e32 v112, v48, v112
	v_mul_f32_e32 v113, v49, v113
	v_mul_f32_e32 v118, v54, v118
	v_mul_f32_e32 v119, v55, v119
	v_mul_f32_e32 v116, v52, v116
	v_mul_f32_e32 v117, v53, v117
	v_mul_f32_e32 v122, v58, v122
	v_mul_f32_e32 v123, v59, v123
	v_mul_f32_e32 v120, v56, v120
	v_mul_f32_e32 v121, v57, v121
	v_mul_f32_e32 v126, v62, v200
	v_mul_f32_e32 v127, v63, v201
	v_mul_f32_e32 v124, v60, v124
	v_mul_f32_e32 v125, v61, v125
	s_cbranch_scc1 .LBB0_182
	v_mul_f32_e32 v66, s60, v66
	v_mul_f32_e32 v67, s60, v67
	v_mul_f32_e32 v64, s60, v64
	v_mul_f32_e32 v65, s60, v65
	v_mul_f32_e32 v70, s60, v70
	v_mul_f32_e32 v71, s60, v71
	v_mul_f32_e32 v68, s60, v68
	v_mul_f32_e32 v69, s60, v69
	v_mul_f32_e32 v74, s60, v74
	v_mul_f32_e32 v75, s60, v75
	v_mul_f32_e32 v72, s60, v72
	v_mul_f32_e32 v73, s60, v73
	v_mul_f32_e32 v78, s60, v78
	v_mul_f32_e32 v79, s60, v79
	v_mul_f32_e32 v76, s60, v76
	v_mul_f32_e32 v77, s60, v77
	v_mul_f32_e32 v82, s60, v82
	v_mul_f32_e32 v83, s60, v83
	v_mul_f32_e32 v80, s60, v80
	v_mul_f32_e32 v81, s60, v81
	v_mul_f32_e32 v86, s60, v86
	v_mul_f32_e32 v87, s60, v87
	v_mul_f32_e32 v84, s60, v84
	v_mul_f32_e32 v85, s60, v85
	v_mul_f32_e32 v90, s60, v90
	v_mul_f32_e32 v91, s60, v91
	v_mul_f32_e32 v88, s60, v88
	v_mul_f32_e32 v89, s60, v89
	v_mul_f32_e32 v94, s60, v94
	v_mul_f32_e32 v95, s60, v95
	v_mul_f32_e32 v92, s60, v92
	v_mul_f32_e32 v93, s60, v93
	v_mul_f32_e32 v98, s60, v98
	v_mul_f32_e32 v99, s60, v99
	v_mul_f32_e32 v96, s60, v96
	v_mul_f32_e32 v97, s60, v97
	v_mul_f32_e32 v102, s60, v102
	v_mul_f32_e32 v103, s60, v103
	v_mul_f32_e32 v100, s60, v100
	v_mul_f32_e32 v101, s60, v101
	v_mul_f32_e32 v106, s60, v106
	v_mul_f32_e32 v107, s60, v107
	v_mul_f32_e32 v104, s60, v104
	v_mul_f32_e32 v105, s60, v105
	v_mul_f32_e32 v110, s60, v110
	v_mul_f32_e32 v111, s60, v111
	v_mul_f32_e32 v108, s60, v108
	v_mul_f32_e32 v109, s60, v109
	v_mul_f32_e32 v114, s60, v114
	v_mul_f32_e32 v115, s60, v115
	v_mul_f32_e32 v112, s60, v112
	v_mul_f32_e32 v113, s60, v113
	v_mul_f32_e32 v118, s60, v118
	v_mul_f32_e32 v119, s60, v119
	v_mul_f32_e32 v116, s60, v116
	v_mul_f32_e32 v117, s60, v117
	v_mul_f32_e32 v122, s60, v122
	v_mul_f32_e32 v123, s60, v123
	v_mul_f32_e32 v120, s60, v120
	v_mul_f32_e32 v121, s60, v121
	v_mul_f32_e32 v126, s60, v126
	v_mul_f32_e32 v127, s60, v127
	v_mul_f32_e32 v124, s60, v124
	v_mul_f32_e32 v125, s60, v125

.Lmy_ip1_epi:
	s_cbranch_scc1 .LBB0_434
	v_mul_f32_e32 v64, 0xbfb8aa3b, v32
	v_exp_f32_e32 v76, v64
	v_mul_f32_e32 v64, 0xbfb8aa3b, v33
	v_exp_f32_e32 v77, v64
	v_mul_f32_e32 v64, 0xbfb8aa3b, v34
	v_exp_f32_e32 v78, v64
	v_mul_f32_e32 v64, 0xbfb8aa3b, v35
	v_add_f32_e32 v76, 1.0, v76
	v_add_f32_e32 v77, 1.0, v77
	v_exp_f32_e32 v79, v64
	v_div_scale_f32 v64, s[56:57], v76, v76, v32
	v_rcp_f32_e32 v80, v64
	v_add_f32_e32 v78, 1.0, v78
	v_add_f32_e32 v79, 1.0, v79
	v_mul_f32_e32 v105, 0xbfb8aa3b, v59
	v_exp_f32_e32 v105, v105
	v_fma_f32 v81, -v64, v80, 1.0
	v_fmac_f32_e32 v80, v81, v80
	v_div_scale_f32 v81, vcc, v32, v76, v32
	v_mul_f32_e32 v82, v81, v80
	v_fma_f32 v83, -v64, v82, v81
	v_fmac_f32_e32 v82, v83, v80
	v_fma_f32 v64, -v64, v82, v81
	v_div_scale_f32 v81, s[56:57], v77, v77, v33
	v_rcp_f32_e32 v83, v81
	v_div_fmas_f32 v64, v64, v80, v82
	v_div_fixup_f32 v76, v64, v76, v32
	s_mov_b64 s[58:59], 0
	v_fma_f32 v64, -v81, v83, 1.0
	v_fmac_f32_e32 v83, v64, v83
	v_div_scale_f32 v64, vcc, v33, v77, v33
	v_mul_f32_e32 v80, v64, v83
	v_fma_f32 v82, -v81, v80, v64
	v_fmac_f32_e32 v80, v82, v83
	v_fma_f32 v64, -v81, v80, v64
	v_div_scale_f32 v81, s[56:57], v78, v78, v34
	v_rcp_f32_e32 v82, v81
	v_div_fmas_f32 v64, v64, v83, v80
	v_div_fixup_f32 v77, v64, v77, v33
	v_fma_f32 v64, -v81, v82, 1.0
	v_fmac_f32_e32 v82, v64, v82
	v_div_scale_f32 v64, vcc, v34, v78, v34
	v_mul_f32_e32 v80, v64, v82
	v_fma_f32 v83, -v81, v80, v64
	v_fmac_f32_e32 v80, v83, v82
	v_fma_f32 v64, -v81, v80, v64
	v_div_scale_f32 v81, s[56:57], v79, v79, v35
	v_rcp_f32_e32 v84, v81
	v_div_fmas_f32 v64, v64, v82, v80
	v_div_fixup_f32 v88, v64, v78, v34
	v_mul_f32_e32 v82, 0xbfb8aa3b, v38
	v_fma_f32 v64, -v81, v84, 1.0
	v_fmac_f32_e32 v84, v64, v84
	v_div_scale_f32 v64, vcc, v35, v79, v35
	v_mul_f32_e32 v78, v64, v84
	v_fma_f32 v80, -v81, v78, v64
	v_fmac_f32_e32 v78, v80, v84
	v_fma_f32 v64, -v81, v78, v64
	v_mul_f32_e32 v80, 0xbfb8aa3b, v36
	v_mul_f32_e32 v81, 0xbfb8aa3b, v37
	v_exp_f32_e32 v80, v80
	v_exp_f32_e32 v81, v81
	v_div_fmas_f32 v64, v64, v84, v78
	v_div_fixup_f32 v89, v64, v79, v35
	v_mul_f32_e32 v83, 0xbfb8aa3b, v39
	v_add_f32_e32 v80, 1.0, v80
	v_add_f32_e32 v81, 1.0, v81
	v_exp_f32_e32 v82, v82
	v_div_scale_f32 v85, s[56:57], v80, v80, v36
	v_rcp_f32_e32 v86, v85
	v_exp_f32_e32 v83, v83
	v_fma_f32 v64, -v85, v86, 1.0
	v_fmac_f32_e32 v86, v64, v86
	v_div_scale_f32 v64, vcc, v36, v80, v36
	v_mul_f32_e32 v78, v64, v86
	v_fma_f32 v79, -v85, v78, v64
	v_fmac_f32_e32 v78, v79, v86
	v_div_scale_f32 v79, s[56:57], v81, v81, v37
	v_rcp_f32_e32 v84, v79
	v_fma_f32 v64, -v85, v78, v64
	v_div_fmas_f32 v64, v64, v86, v78
	v_div_fixup_f32 v78, v64, v80, v36
	v_fma_f32 v64, -v79, v84, 1.0
	v_fmac_f32_e32 v84, v64, v84
	v_div_scale_f32 v64, vcc, v37, v81, v37
	v_mul_f32_e32 v80, v64, v84
	v_add_f32_e32 v82, 1.0, v82
	v_add_f32_e32 v83, 1.0, v83
	v_fma_f32 v85, -v79, v80, v64
	v_fmac_f32_e32 v80, v85, v84
	v_div_scale_f32 v85, s[56:57], v82, v82, v38
	v_rcp_f32_e32 v86, v85
	v_fma_f32 v64, -v79, v80, v64
	v_div_fmas_f32 v64, v64, v84, v80
	v_div_fixup_f32 v79, v64, v81, v37
	v_fma_f32 v64, -v85, v86, 1.0
	v_fmac_f32_e32 v86, v64, v86
	v_div_scale_f32 v64, vcc, v38, v82, v38
	v_mul_f32_e32 v80, v64, v86
	v_fma_f32 v81, -v85, v80, v64
	v_fmac_f32_e32 v80, v81, v86
	v_div_scale_f32 v81, s[56:57], v83, v83, v39
	v_rcp_f32_e32 v87, v81
	v_fma_f32 v64, -v85, v80, v64
	v_div_fmas_f32 v64, v64, v86, v80
	v_div_fixup_f32 v92, v64, v82, v38
	v_fma_f32 v64, -v81, v87, 1.0
	v_fmac_f32_e32 v87, v64, v87
	v_div_scale_f32 v64, vcc, v39, v83, v39
	v_mul_f32_e32 v82, v64, v87
	v_fma_f32 v80, -v81, v82, v64
	v_fmac_f32_e32 v82, v80, v87
	v_fma_f32 v64, -v81, v82, v64
	v_mul_f32_e32 v80, 0xbfb8aa3b, v40
	v_mul_f32_e32 v81, 0xbfb8aa3b, v41
	v_exp_f32_e32 v80, v80
	v_exp_f32_e32 v81, v81
	v_mul_f32_e32 v84, 0xbfb8aa3b, v42
	v_mul_f32_e32 v85, 0xbfb8aa3b, v43
	v_exp_f32_e32 v84, v84
	v_add_f32_e32 v80, 1.0, v80
	v_add_f32_e32 v81, 1.0, v81
	v_exp_f32_e32 v85, v85
	v_div_scale_f32 v86, s[56:57], v80, v80, v40
	v_rcp_f32_e32 v90, v86
	v_div_fmas_f32 v64, v64, v87, v82
	v_div_fixup_f32 v93, v64, v83, v39
	v_add_f32_e32 v82, 1.0, v84
	v_add_f32_e32 v83, 1.0, v85
	v_fma_f32 v64, -v86, v90, 1.0
	v_fmac_f32_e32 v90, v64, v90
	v_div_scale_f32 v64, vcc, v40, v80, v40
	v_mul_f32_e32 v84, v64, v90
	v_fma_f32 v85, -v86, v84, v64
	v_fmac_f32_e32 v84, v85, v90
	v_div_scale_f32 v85, s[56:57], v81, v81, v41
	v_fma_f32 v64, -v86, v84, v64
	v_rcp_f32_e32 v86, v85
	v_div_fmas_f32 v64, v64, v90, v84
	v_div_fixup_f32 v80, v64, v80, v40
	v_fma_f32 v64, -v85, v86, 1.0
	v_fmac_f32_e32 v86, v64, v86
	v_div_scale_f32 v64, vcc, v41, v81, v41
	v_mul_f32_e32 v84, v64, v86
	v_fma_f32 v87, -v85, v84, v64
	v_fmac_f32_e32 v84, v87, v86
	v_fma_f32 v64, -v85, v84, v64
	v_div_scale_f32 v85, s[56:57], v82, v82, v42
	v_rcp_f32_e32 v87, v85
	v_div_fmas_f32 v64, v64, v86, v84
	v_div_fixup_f32 v81, v64, v81, v41
	v_fma_f32 v64, -v85, v87, 1.0
	v_fmac_f32_e32 v87, v64, v87
	v_div_scale_f32 v64, vcc, v42, v82, v42
	v_mul_f32_e32 v84, v64, v87
	v_fma_f32 v86, -v85, v84, v64
	v_fmac_f32_e32 v84, v86, v87
	v_fma_f32 v64, -v85, v84, v64
	v_div_scale_f32 v85, s[56:57], v83, v83, v43
	v_rcp_f32_e32 v90, v85
	v_div_fmas_f32 v64, v64, v87, v84
	v_div_fixup_f32 v96, v64, v82, v42
	v_mul_f32_e32 v86, 0xbfb8aa3b, v46
	v_fma_f32 v64, -v85, v90, 1.0
	v_fmac_f32_e32 v90, v64, v90
	v_div_scale_f32 v64, vcc, v43, v83, v43
	v_mul_f32_e32 v82, v64, v90
	v_fma_f32 v84, -v85, v82, v64
	v_fmac_f32_e32 v82, v84, v90
	v_fma_f32 v64, -v85, v82, v64
	v_mul_f32_e32 v84, 0xbfb8aa3b, v44
	v_mul_f32_e32 v85, 0xbfb8aa3b, v45
	v_exp_f32_e32 v84, v84
	v_exp_f32_e32 v85, v85
	v_div_fmas_f32 v64, v64, v90, v82
	v_div_fixup_f32 v97, v64, v83, v43
	v_mul_f32_e32 v87, 0xbfb8aa3b, v47
	v_add_f32_e32 v84, 1.0, v84
	v_add_f32_e32 v85, 1.0, v85
	v_exp_f32_e32 v86, v86
	v_div_scale_f32 v91, s[56:57], v84, v84, v44
	v_rcp_f32_e32 v94, v91
	v_exp_f32_e32 v87, v87
	v_fma_f32 v64, -v91, v94, 1.0
	v_fmac_f32_e32 v94, v64, v94
	v_div_scale_f32 v64, vcc, v44, v84, v44
	v_mul_f32_e32 v82, v64, v94
	v_fma_f32 v83, -v91, v82, v64
	v_fmac_f32_e32 v82, v83, v94
	v_div_scale_f32 v83, s[56:57], v85, v85, v45
	v_rcp_f32_e32 v90, v83
	v_fma_f32 v64, -v91, v82, v64
	v_div_fmas_f32 v64, v64, v94, v82
	v_div_fixup_f32 v82, v64, v84, v44
	v_fma_f32 v64, -v83, v90, 1.0
	v_fmac_f32_e32 v90, v64, v90
	v_div_scale_f32 v64, vcc, v45, v85, v45
	v_mul_f32_e32 v84, v64, v90
	v_add_f32_e32 v86, 1.0, v86
	v_add_f32_e32 v87, 1.0, v87
	v_fma_f32 v91, -v83, v84, v64
	v_fmac_f32_e32 v84, v91, v90
	v_div_scale_f32 v91, s[56:57], v86, v86, v46
	v_rcp_f32_e32 v94, v91
	v_fma_f32 v64, -v83, v84, v64
	v_div_fmas_f32 v64, v64, v90, v84
	v_div_fixup_f32 v83, v64, v85, v45
	v_fma_f32 v64, -v91, v94, 1.0
	v_fmac_f32_e32 v94, v64, v94
	v_div_scale_f32 v64, vcc, v46, v86, v46
	v_mul_f32_e32 v84, v64, v94
	v_fma_f32 v85, -v91, v84, v64
	v_fmac_f32_e32 v84, v85, v94
	v_div_scale_f32 v85, s[56:57], v87, v87, v47
	v_rcp_f32_e32 v95, v85
	v_fma_f32 v64, -v91, v84, v64
	v_div_fmas_f32 v64, v64, v94, v84
	v_div_fixup_f32 v98, v64, v86, v46
	v_fma_f32 v64, -v85, v95, 1.0
	v_fmac_f32_e32 v95, v64, v95
	v_div_scale_f32 v64, vcc, v47, v87, v47
	v_mul_f32_e32 v86, v64, v95
	v_fma_f32 v84, -v85, v86, v64
	v_fmac_f32_e32 v86, v84, v95
	v_fma_f32 v64, -v85, v86, v64
	v_mul_f32_e32 v84, 0xbfb8aa3b, v48
	v_mul_f32_e32 v85, 0xbfb8aa3b, v49
	v_exp_f32_e32 v84, v84
	v_exp_f32_e32 v85, v85
	v_mul_f32_e32 v90, 0xbfb8aa3b, v50
	v_mul_f32_e32 v91, 0xbfb8aa3b, v51
	v_exp_f32_e32 v90, v90
	v_add_f32_e32 v84, 1.0, v84
	v_add_f32_e32 v85, 1.0, v85
	v_exp_f32_e32 v91, v91
	v_div_scale_f32 v94, s[56:57], v84, v84, v48
	v_rcp_f32_e32 v100, v94
	v_div_fmas_f32 v64, v64, v95, v86
	v_div_fixup_f32 v99, v64, v87, v47
	v_add_f32_e32 v86, 1.0, v90
	v_add_f32_e32 v87, 1.0, v91
	v_fma_f32 v64, -v94, v100, 1.0
	v_fmac_f32_e32 v100, v64, v100
	v_div_scale_f32 v64, vcc, v48, v84, v48
	v_mul_f32_e32 v90, v64, v100
	v_fma_f32 v91, -v94, v90, v64
	v_fmac_f32_e32 v90, v91, v100
	v_div_scale_f32 v91, s[56:57], v85, v85, v49
	v_fma_f32 v64, -v94, v90, v64
	v_rcp_f32_e32 v94, v91
	v_div_fmas_f32 v64, v64, v100, v90
	v_div_fixup_f32 v84, v64, v84, v48
	v_fma_f32 v64, -v91, v94, 1.0
	v_fmac_f32_e32 v94, v64, v94
	v_div_scale_f32 v64, vcc, v49, v85, v49
	v_mul_f32_e32 v90, v64, v94
	v_fma_f32 v95, -v91, v90, v64
	v_fmac_f32_e32 v90, v95, v94
	v_fma_f32 v64, -v91, v90, v64
	v_div_scale_f32 v91, s[56:57], v86, v86, v50
	v_rcp_f32_e32 v95, v91
	v_div_fmas_f32 v64, v64, v94, v90
	v_div_fixup_f32 v85, v64, v85, v49
	v_fma_f32 v64, -v91, v95, 1.0
	v_fmac_f32_e32 v95, v64, v95
	v_div_scale_f32 v64, vcc, v50, v86, v50
	v_mul_f32_e32 v90, v64, v95
	v_fma_f32 v94, -v91, v90, v64
	v_fmac_f32_e32 v90, v94, v95
	v_fma_f32 v64, -v91, v90, v64
	v_div_scale_f32 v91, s[56:57], v87, v87, v51
	v_rcp_f32_e32 v101, v91
	v_div_fmas_f32 v64, v64, v95, v90
	v_div_fixup_f32 v100, v64, v86, v50
	v_mul_f32_e32 v94, 0xbfb8aa3b, v54
	v_fma_f32 v64, -v91, v101, 1.0
	v_fmac_f32_e32 v101, v64, v101
	v_div_scale_f32 v64, vcc, v51, v87, v51
	v_mul_f32_e32 v86, v64, v101
	v_fma_f32 v90, -v91, v86, v64
	v_fmac_f32_e32 v86, v90, v101
	v_fma_f32 v64, -v91, v86, v64
	v_mul_f32_e32 v90, 0xbfb8aa3b, v52
	v_mul_f32_e32 v91, 0xbfb8aa3b, v53
	v_exp_f32_e32 v90, v90
	v_exp_f32_e32 v91, v91
	v_div_fmas_f32 v64, v64, v101, v86
	v_div_fixup_f32 v101, v64, v87, v51
	v_mul_f32_e32 v95, 0xbfb8aa3b, v55
	v_add_f32_e32 v90, 1.0, v90
	v_add_f32_e32 v91, 1.0, v91
	v_exp_f32_e32 v94, v94
	v_div_scale_f32 v102, s[56:57], v90, v90, v52
	v_rcp_f32_e32 v103, v102
	v_exp_f32_e32 v95, v95
	v_fma_f32 v64, -v102, v103, 1.0
	v_fmac_f32_e32 v103, v64, v103
	v_div_scale_f32 v64, vcc, v52, v90, v52
	v_mul_f32_e32 v86, v64, v103
	v_fma_f32 v87, -v102, v86, v64
	v_fmac_f32_e32 v86, v87, v103
	v_div_scale_f32 v87, s[56:57], v91, v91, v53
	v_fma_f32 v64, -v102, v86, v64
	v_rcp_f32_e32 v102, v87
	v_div_fmas_f32 v64, v64, v103, v86
	v_div_fixup_f32 v86, v64, v90, v52
	v_add_f32_e32 v94, 1.0, v94
	v_add_f32_e32 v95, 1.0, v95
	v_fma_f32 v64, -v87, v102, 1.0
	v_fmac_f32_e32 v102, v64, v102
	v_div_scale_f32 v64, vcc, v53, v91, v53
	v_mul_f32_e32 v90, v64, v102
	v_fma_f32 v103, -v87, v90, v64
	v_fmac_f32_e32 v90, v103, v102
	v_div_scale_f32 v103, s[56:57], v94, v94, v54
	v_rcp_f32_e32 v104, v103
	v_fma_f32 v64, -v87, v90, v64
	v_div_fmas_f32 v64, v64, v102, v90
	v_div_fixup_f32 v87, v64, v91, v53
	v_fma_f32 v64, -v103, v104, 1.0
	v_fmac_f32_e32 v104, v64, v104
	v_div_scale_f32 v64, vcc, v54, v94, v54
	v_mul_f32_e32 v90, v64, v104
	v_fma_f32 v91, -v103, v90, v64
	v_fmac_f32_e32 v90, v91, v104
	v_div_scale_f32 v91, s[56:57], v95, v95, v55
	v_fma_f32 v64, -v103, v90, v64
	v_rcp_f32_e32 v103, v91
	v_div_fmas_f32 v64, v64, v104, v90
	v_div_fixup_f32 v102, v64, v94, v54
	v_mul_f32_e32 v104, 0xbfb8aa3b, v58
	v_fma_f32 v64, -v91, v103, 1.0
	v_fmac_f32_e32 v103, v64, v103
	v_div_scale_f32 v64, vcc, v55, v95, v55
	v_mul_f32_e32 v94, v64, v103
	v_fma_f32 v90, -v91, v94, v64
	v_fmac_f32_e32 v94, v90, v103
	v_fma_f32 v64, -v91, v94, v64
	v_mul_f32_e32 v90, 0xbfb8aa3b, v56
	v_mul_f32_e32 v91, 0xbfb8aa3b, v57
	v_exp_f32_e32 v90, v90
	v_exp_f32_e32 v91, v91
	v_exp_f32_e32 v104, v104
	v_div_fmas_f32 v64, v64, v103, v94
	v_div_fixup_f32 v103, v64, v95, v55
	v_add_f32_e32 v90, 1.0, v90
	v_add_f32_e32 v91, 1.0, v91
	v_add_f32_e32 v94, 1.0, v104
	v_add_f32_e32 v95, 1.0, v105
	v_div_scale_f32 v106, s[56:57], v90, v90, v56
	v_rcp_f32_e32 v107, v106
	s_nop 0
	v_fma_f32 v64, -v106, v107, 1.0
	v_fmac_f32_e32 v107, v64, v107
	v_div_scale_f32 v64, vcc, v56, v90, v56
	v_mul_f32_e32 v104, v64, v107
	v_fma_f32 v105, -v106, v104, v64
	v_fmac_f32_e32 v104, v105, v107
	v_div_scale_f32 v105, s[56:57], v91, v91, v57
	v_fma_f32 v64, -v106, v104, v64
	v_rcp_f32_e32 v106, v105
	v_div_fmas_f32 v64, v64, v107, v104
	v_div_fixup_f32 v90, v64, v90, v56
	v_fma_f32 v64, -v105, v106, 1.0
	v_fmac_f32_e32 v106, v64, v106
	v_div_scale_f32 v64, vcc, v57, v91, v57
	v_mul_f32_e32 v104, v64, v106
	v_fma_f32 v107, -v105, v104, v64
	v_fmac_f32_e32 v104, v107, v106
	v_fma_f32 v64, -v105, v104, v64
	v_div_scale_f32 v105, s[56:57], v94, v94, v58
	v_rcp_f32_e32 v107, v105
	v_div_fmas_f32 v64, v64, v106, v104
	v_div_fixup_f32 v91, v64, v91, v57
	v_fma_f32 v64, -v105, v107, 1.0
	v_fmac_f32_e32 v107, v64, v107
	v_div_scale_f32 v64, vcc, v58, v94, v58
	v_mul_f32_e32 v104, v64, v107
	v_fma_f32 v106, -v105, v104, v64
	v_fmac_f32_e32 v104, v106, v107
	v_fma_f32 v64, -v105, v104, v64
	v_div_scale_f32 v105, s[56:57], v95, v95, v59
	v_rcp_f32_e32 v110, v105
	v_div_fmas_f32 v64, v64, v107, v104
	v_div_fixup_f32 v104, v64, v94, v58
	v_fma_f32 v64, -v105, v110, 1.0
	v_fmac_f32_e32 v110, v64, v110
	v_div_scale_f32 v64, vcc, v59, v95, v59
	v_mul_f32_e32 v94, v64, v110
	v_fma_f32 v106, -v105, v94, v64
	v_fmac_f32_e32 v94, v106, v110
	v_fma_f32 v64, -v105, v94, v64
	v_mul_f32_e32 v105, 0xbfb8aa3b, v60
	v_exp_f32_e32 v106, v105
	v_mul_f32_e32 v105, 0xbfb8aa3b, v61
	v_exp_f32_e32 v107, v105
	v_mul_f32_e32 v105, 0xbfb8aa3b, v62
	v_exp_f32_e32 v108, v105
	v_mul_f32_e32 v105, 0xbfb8aa3b, v63
	v_add_f32_e32 v106, 1.0, v106
	v_add_f32_e32 v107, 1.0, v107
	v_div_fmas_f32 v64, v64, v110, v94
	v_div_scale_f32 v111, s[56:57], v106, v106, v60
	v_rcp_f32_e32 v112, v111
	v_exp_f32_e32 v109, v105
	v_div_fixup_f32 v105, v64, v95, v59
	v_fma_f32 v64, -v111, v112, 1.0
	v_fmac_f32_e32 v112, v64, v112
	v_div_scale_f32 v64, vcc, v60, v106, v60
	v_mul_f32_e32 v94, v64, v112
	v_fma_f32 v95, -v111, v94, v64
	v_fmac_f32_e32 v94, v95, v112
	v_div_scale_f32 v95, s[56:57], v107, v107, v61
	v_rcp_f32_e32 v110, v95
	v_fma_f32 v64, -v111, v94, v64
	v_div_fmas_f32 v64, v64, v112, v94
	v_div_fixup_f32 v94, v64, v106, v60
	v_fma_f32 v64, -v95, v110, 1.0
	v_fmac_f32_e32 v110, v64, v110
	v_div_scale_f32 v64, vcc, v61, v107, v61
	v_mul_f32_e32 v106, v64, v110
	v_add_f32_e32 v108, 1.0, v108
	v_add_f32_e32 v109, 1.0, v109
	v_fma_f32 v111, -v95, v106, v64
	v_fmac_f32_e32 v106, v111, v110
	v_div_scale_f32 v111, s[56:57], v108, v108, v62
	v_rcp_f32_e32 v112, v111
	v_fma_f32 v64, -v95, v106, v64
	v_div_fmas_f32 v64, v64, v110, v106
	v_div_fixup_f32 v95, v64, v107, v61
	v_fma_f32 v64, -v111, v112, 1.0
	v_fmac_f32_e32 v112, v64, v112
	v_div_scale_f32 v64, vcc, v62, v108, v62
	v_mul_f32_e32 v106, v64, v112
	v_fma_f32 v107, -v111, v106, v64
	v_fmac_f32_e32 v106, v107, v112
	v_div_scale_f32 v107, s[56:57], v109, v109, v63
	v_rcp_f32_e32 v114, v107
	v_fma_f32 v64, -v111, v106, v64
	v_div_fmas_f32 v64, v64, v112, v106
	v_div_fixup_f32 v106, v64, v108, v62
	v_fma_f32 v64, -v107, v114, 1.0
	v_fmac_f32_e32 v114, v64, v114
	v_div_scale_f32 v64, vcc, v63, v109, v63
	v_mul_f32_e32 v108, v64, v114
	v_fma_f32 v110, -v107, v108, v64
	v_fmac_f32_e32 v108, v110, v114
	v_fma_f32 v64, -v107, v108, v64
	v_mul_f32_e32 v107, 0xbfb8aa3b, v4
	v_exp_f32_e32 v110, v107
	v_mul_f32_e32 v107, 0xbfb8aa3b, v5
	v_exp_f32_e32 v111, v107
	v_mul_f32_e32 v107, 0xbfb8aa3b, v6
	v_exp_f32_e32 v112, v107
	v_mul_f32_e32 v107, 0xbfb8aa3b, v7
	v_add_f32_e32 v110, 1.0, v110
	v_add_f32_e32 v111, 1.0, v111
	v_div_fmas_f32 v64, v64, v114, v108
	v_div_scale_f32 v115, s[56:57], v110, v110, v4
	v_rcp_f32_e32 v116, v115
	v_exp_f32_e32 v113, v107
	v_div_fixup_f32 v107, v64, v109, v63
	v_fma_f32 v64, -v115, v116, 1.0
	v_fmac_f32_e32 v116, v64, v116
	v_div_scale_f32 v64, vcc, v4, v110, v4
	v_mul_f32_e32 v108, v64, v116
	v_fma_f32 v109, -v115, v108, v64
	v_fmac_f32_e32 v108, v109, v116
	v_div_scale_f32 v109, s[56:57], v111, v111, v5
	v_rcp_f32_e32 v114, v109
	v_fma_f32 v64, -v115, v108, v64
	v_div_fmas_f32 v64, v64, v116, v108
	v_div_fixup_f32 v108, v64, v110, v4
	v_fma_f32 v64, -v109, v114, 1.0
	v_fmac_f32_e32 v114, v64, v114
	v_div_scale_f32 v64, vcc, v5, v111, v5
	v_mul_f32_e32 v110, v64, v114
	v_add_f32_e32 v112, 1.0, v112
	v_add_f32_e32 v113, 1.0, v113
	v_fma_f32 v115, -v109, v110, v64
	v_fmac_f32_e32 v110, v115, v114
	v_div_scale_f32 v115, s[56:57], v112, v112, v6
	v_rcp_f32_e32 v116, v115
	v_fma_f32 v64, -v109, v110, v64
	v_div_fmas_f32 v64, v64, v114, v110
	v_div_fixup_f32 v109, v64, v111, v5
	v_fma_f32 v64, -v115, v116, 1.0
	v_fmac_f32_e32 v116, v64, v116
	v_div_scale_f32 v64, vcc, v6, v112, v6
	v_mul_f32_e32 v110, v64, v116
	v_fma_f32 v111, -v115, v110, v64
	v_fmac_f32_e32 v110, v111, v116
	v_div_scale_f32 v111, s[56:57], v113, v113, v7
	v_rcp_f32_e32 v117, v111
	v_fma_f32 v64, -v115, v110, v64
	v_div_fmas_f32 v64, v64, v116, v110
	v_div_fixup_f32 v120, v64, v112, v6
	v_fma_f32 v64, -v111, v117, 1.0
	v_fmac_f32_e32 v117, v64, v117
	v_div_scale_f32 v64, vcc, v7, v113, v7
	v_mul_f32_e32 v112, v64, v117
	v_fma_f32 v110, -v111, v112, v64
	v_fmac_f32_e32 v112, v110, v117
	v_fma_f32 v64, -v111, v112, v64
	v_mul_f32_e32 v110, 0xbfb8aa3b, v12
	v_mul_f32_e32 v111, 0xbfb8aa3b, v13
	v_exp_f32_e32 v110, v110
	v_exp_f32_e32 v111, v111
	v_mul_f32_e32 v114, 0xbfb8aa3b, v14
	v_mul_f32_e32 v115, 0xbfb8aa3b, v15
	v_exp_f32_e32 v114, v114
	v_add_f32_e32 v110, 1.0, v110
	v_add_f32_e32 v111, 1.0, v111
	v_exp_f32_e32 v115, v115
	v_div_scale_f32 v116, s[56:57], v110, v110, v12
	v_rcp_f32_e32 v118, v116
	v_div_fmas_f32 v64, v64, v117, v112
	v_div_fixup_f32 v121, v64, v113, v7
	v_add_f32_e32 v112, 1.0, v114
	v_add_f32_e32 v113, 1.0, v115
	v_fma_f32 v64, -v116, v118, 1.0
	v_fmac_f32_e32 v118, v64, v118
	v_div_scale_f32 v64, vcc, v12, v110, v12
	v_mul_f32_e32 v114, v64, v118
	v_fma_f32 v115, -v116, v114, v64
	v_fmac_f32_e32 v114, v115, v118
	v_div_scale_f32 v115, s[56:57], v111, v111, v13
	v_fma_f32 v64, -v116, v114, v64
	v_rcp_f32_e32 v116, v115
	v_div_fmas_f32 v64, v64, v118, v114
	v_div_fixup_f32 v110, v64, v110, v12
	v_fma_f32 v64, -v115, v116, 1.0
	v_fmac_f32_e32 v116, v64, v116
	v_div_scale_f32 v64, vcc, v13, v111, v13
	v_mul_f32_e32 v114, v64, v116
	v_fma_f32 v117, -v115, v114, v64
	v_fmac_f32_e32 v114, v117, v116
	v_fma_f32 v64, -v115, v114, v64
	v_div_scale_f32 v115, s[56:57], v112, v112, v14
	v_rcp_f32_e32 v117, v115
	v_div_fmas_f32 v64, v64, v116, v114
	v_div_fixup_f32 v111, v64, v111, v13
	v_fma_f32 v64, -v115, v117, 1.0
	v_fmac_f32_e32 v117, v64, v117
	v_div_scale_f32 v64, vcc, v14, v112, v14
	v_mul_f32_e32 v114, v64, v117
	v_fma_f32 v116, -v115, v114, v64
	v_fmac_f32_e32 v114, v116, v117
	v_fma_f32 v64, -v115, v114, v64
	v_div_scale_f32 v115, s[56:57], v113, v113, v15
	v_rcp_f32_e32 v118, v115
	v_div_fmas_f32 v64, v64, v117, v114
	v_div_fixup_f32 v124, v64, v112, v14
	v_mul_f32_e32 v116, 0xbfb8aa3b, v18
	v_fma_f32 v64, -v115, v118, 1.0
	v_fmac_f32_e32 v118, v64, v118
	v_div_scale_f32 v64, vcc, v15, v113, v15
	v_mul_f32_e32 v112, v64, v118
	v_fma_f32 v114, -v115, v112, v64
	v_fmac_f32_e32 v112, v114, v118
	v_fma_f32 v64, -v115, v112, v64
	v_mul_f32_e32 v114, 0xbfb8aa3b, v16
	v_mul_f32_e32 v115, 0xbfb8aa3b, v17
	v_exp_f32_e32 v114, v114
	v_exp_f32_e32 v115, v115
	v_div_fmas_f32 v64, v64, v118, v112
	v_div_fixup_f32 v125, v64, v113, v15
	v_mul_f32_e32 v117, 0xbfb8aa3b, v19
	v_add_f32_e32 v114, 1.0, v114
	v_add_f32_e32 v115, 1.0, v115
	v_exp_f32_e32 v116, v116
	v_div_scale_f32 v119, s[56:57], v114, v114, v16
	v_rcp_f32_e32 v122, v119
	v_exp_f32_e32 v117, v117
	v_fma_f32 v64, -v119, v122, 1.0
	v_fmac_f32_e32 v122, v64, v122
	v_div_scale_f32 v64, vcc, v16, v114, v16
	v_mul_f32_e32 v112, v64, v122
	v_fma_f32 v113, -v119, v112, v64
	v_fmac_f32_e32 v112, v113, v122
	v_div_scale_f32 v113, s[56:57], v115, v115, v17
	v_rcp_f32_e32 v118, v113
	v_fma_f32 v64, -v119, v112, v64
	v_div_fmas_f32 v64, v64, v122, v112
	v_div_fixup_f32 v112, v64, v114, v16
	v_fma_f32 v64, -v113, v118, 1.0
	v_fmac_f32_e32 v118, v64, v118
	v_div_scale_f32 v64, vcc, v17, v115, v17
	v_mul_f32_e32 v114, v64, v118
	v_add_f32_e32 v116, 1.0, v116
	v_add_f32_e32 v117, 1.0, v117
	v_fma_f32 v119, -v113, v114, v64
	v_fmac_f32_e32 v114, v119, v118
	v_div_scale_f32 v119, s[56:57], v116, v116, v18
	v_rcp_f32_e32 v122, v119
	v_fma_f32 v64, -v113, v114, v64
	v_div_fmas_f32 v64, v64, v118, v114
	v_div_fixup_f32 v113, v64, v115, v17
	v_fma_f32 v64, -v119, v122, 1.0
	v_fmac_f32_e32 v122, v64, v122
	v_div_scale_f32 v64, vcc, v18, v116, v18
	v_mul_f32_e32 v114, v64, v122
	v_fma_f32 v115, -v119, v114, v64
	v_fmac_f32_e32 v114, v115, v122
	v_div_scale_f32 v115, s[56:57], v117, v117, v19
	v_rcp_f32_e32 v123, v115
	v_fma_f32 v64, -v119, v114, v64
	v_div_fmas_f32 v64, v64, v122, v114
	v_div_fixup_f32 v140, v64, v116, v18
	v_fma_f32 v64, -v115, v123, 1.0
	v_fmac_f32_e32 v123, v64, v123
	v_div_scale_f32 v64, vcc, v19, v117, v19
	v_mul_f32_e32 v116, v64, v123
	v_fma_f32 v114, -v115, v116, v64
	v_fmac_f32_e32 v116, v114, v123
	v_fma_f32 v64, -v115, v116, v64
	v_mul_f32_e32 v114, 0xbfb8aa3b, v20
	v_mul_f32_e32 v115, 0xbfb8aa3b, v21
	v_exp_f32_e32 v114, v114
	v_exp_f32_e32 v115, v115
	v_mul_f32_e32 v118, 0xbfb8aa3b, v22
	v_mul_f32_e32 v119, 0xbfb8aa3b, v23
	v_exp_f32_e32 v118, v118
	v_add_f32_e32 v114, 1.0, v114
	v_add_f32_e32 v115, 1.0, v115
	v_exp_f32_e32 v119, v119
	v_div_scale_f32 v122, s[56:57], v114, v114, v20
	v_rcp_f32_e32 v126, v122
	v_div_fmas_f32 v64, v64, v123, v116
	v_div_fixup_f32 v141, v64, v117, v19
	v_add_f32_e32 v116, 1.0, v118
	v_add_f32_e32 v117, 1.0, v119
	v_fma_f32 v64, -v122, v126, 1.0
	v_fmac_f32_e32 v126, v64, v126
	v_div_scale_f32 v64, vcc, v20, v114, v20
	v_mul_f32_e32 v118, v64, v126
	v_fma_f32 v119, -v122, v118, v64
	v_fmac_f32_e32 v118, v119, v126
	v_div_scale_f32 v119, s[56:57], v115, v115, v21
	v_fma_f32 v64, -v122, v118, v64
	v_rcp_f32_e32 v122, v119
	v_div_fmas_f32 v64, v64, v126, v118
	v_div_fixup_f32 v114, v64, v114, v20
	v_fma_f32 v64, -v119, v122, 1.0
	v_fmac_f32_e32 v122, v64, v122
	v_div_scale_f32 v64, vcc, v21, v115, v21
	v_mul_f32_e32 v118, v64, v122
	v_fma_f32 v123, -v119, v118, v64
	v_fmac_f32_e32 v118, v123, v122
	v_fma_f32 v64, -v119, v118, v64
	v_div_scale_f32 v119, s[56:57], v116, v116, v22
	v_rcp_f32_e32 v123, v119
	v_div_fmas_f32 v64, v64, v122, v118
	v_div_fixup_f32 v115, v64, v115, v21
	v_fma_f32 v64, -v119, v123, 1.0
	v_fmac_f32_e32 v123, v64, v123
	v_div_scale_f32 v64, vcc, v22, v116, v22
	v_mul_f32_e32 v118, v64, v123
	v_fma_f32 v122, -v119, v118, v64
	v_fmac_f32_e32 v118, v122, v123
	v_fma_f32 v64, -v119, v118, v64
	v_div_scale_f32 v119, s[56:57], v117, v117, v23
	v_rcp_f32_e32 v126, v119
	v_div_fmas_f32 v64, v64, v123, v118
	v_div_fixup_f32 v142, v64, v116, v22
	v_mul_f32_e32 v122, 0xbfb8aa3b, v2
	v_fma_f32 v64, -v119, v126, 1.0
	v_fmac_f32_e32 v126, v64, v126
	v_div_scale_f32 v64, vcc, v23, v117, v23
	v_mul_f32_e32 v116, v64, v126
	v_fma_f32 v118, -v119, v116, v64
	v_fmac_f32_e32 v116, v118, v126
	v_fma_f32 v64, -v119, v116, v64
	v_mul_f32_e32 v118, 0xbfb8aa3b, v0
	v_mul_f32_e32 v119, 0xbfb8aa3b, v1
	v_exp_f32_e32 v118, v118
	v_exp_f32_e32 v119, v119
	v_div_fmas_f32 v64, v64, v126, v116
	v_div_fixup_f32 v143, v64, v117, v23
	v_mul_f32_e32 v123, 0xbfb8aa3b, v3
	v_add_f32_e32 v118, 1.0, v118
	v_add_f32_e32 v119, 1.0, v119
	v_exp_f32_e32 v122, v122
	v_div_scale_f32 v127, s[56:57], v118, v118, v0
	v_rcp_f32_e32 v144, v127
	v_exp_f32_e32 v123, v123
	v_fma_f32 v64, -v127, v144, 1.0
	v_fmac_f32_e32 v144, v64, v144
	v_div_scale_f32 v64, vcc, v0, v118, v0
	v_mul_f32_e32 v116, v64, v144
	v_fma_f32 v117, -v127, v116, v64
	v_fmac_f32_e32 v116, v117, v144
	v_div_scale_f32 v117, s[56:57], v119, v119, v1
	v_rcp_f32_e32 v126, v117
	v_fma_f32 v64, -v127, v116, v64
	v_div_fmas_f32 v64, v64, v144, v116
	v_div_fixup_f32 v116, v64, v118, v0
	v_fma_f32 v64, -v117, v126, 1.0
	v_fmac_f32_e32 v126, v64, v126
	v_div_scale_f32 v64, vcc, v1, v119, v1
	v_mul_f32_e32 v118, v64, v126
	v_add_f32_e32 v122, 1.0, v122
	v_add_f32_e32 v123, 1.0, v123
	v_fma_f32 v127, -v117, v118, v64
	v_fmac_f32_e32 v118, v127, v126
	v_div_scale_f32 v127, s[56:57], v122, v122, v2
	v_rcp_f32_e32 v144, v127
	v_fma_f32 v64, -v117, v118, v64
	v_div_fmas_f32 v64, v64, v126, v118
	v_div_fixup_f32 v117, v64, v119, v1
	v_fma_f32 v64, -v127, v144, 1.0
	v_fmac_f32_e32 v144, v64, v144
	v_div_scale_f32 v64, vcc, v2, v122, v2
	v_mul_f32_e32 v118, v64, v144
	v_fma_f32 v119, -v127, v118, v64
	v_fmac_f32_e32 v118, v119, v144
	v_div_scale_f32 v119, s[56:57], v123, v123, v3
	v_rcp_f32_e32 v145, v119
	v_fma_f32 v64, -v127, v118, v64
	v_div_fmas_f32 v64, v64, v144, v118
	v_div_fixup_f32 v144, v64, v122, v2
	v_fma_f32 v64, -v119, v145, 1.0
	v_fmac_f32_e32 v145, v64, v145
	v_div_scale_f32 v64, vcc, v3, v123, v3
	v_mul_f32_e32 v122, v64, v145
	v_fma_f32 v118, -v119, v122, v64
	v_fmac_f32_e32 v122, v118, v145
	v_fma_f32 v64, -v119, v122, v64
	v_mul_f32_e32 v118, 0xbfb8aa3b, v8
	v_mul_f32_e32 v119, 0xbfb8aa3b, v9
	v_exp_f32_e32 v118, v118
	v_exp_f32_e32 v119, v119
	v_mul_f32_e32 v126, 0xbfb8aa3b, v10
	v_mul_f32_e32 v127, 0xbfb8aa3b, v11
	v_exp_f32_e32 v126, v126
	v_add_f32_e32 v118, 1.0, v118
	v_add_f32_e32 v119, 1.0, v119
	v_exp_f32_e32 v127, v127
	v_div_scale_f32 v146, s[56:57], v118, v118, v8
	v_rcp_f32_e32 v147, v146
	v_div_fmas_f32 v64, v64, v145, v122
	v_div_fixup_f32 v145, v64, v123, v3
	v_add_f32_e32 v122, 1.0, v126
	v_add_f32_e32 v123, 1.0, v127
	v_fma_f32 v64, -v146, v147, 1.0
	v_fmac_f32_e32 v147, v64, v147
	v_div_scale_f32 v64, vcc, v8, v118, v8
	v_mul_f32_e32 v126, v64, v147
	v_fma_f32 v127, -v146, v126, v64
	v_fmac_f32_e32 v126, v127, v147
	v_div_scale_f32 v127, s[56:57], v119, v119, v9
	v_fma_f32 v64, -v146, v126, v64
	v_rcp_f32_e32 v146, v127
	v_div_fmas_f32 v64, v64, v147, v126
	v_div_fixup_f32 v118, v64, v118, v8
	v_fma_f32 v64, -v127, v146, 1.0
	v_fmac_f32_e32 v146, v64, v146
	v_div_scale_f32 v64, vcc, v9, v119, v9
	v_mul_f32_e32 v126, v64, v146
	v_fma_f32 v147, -v127, v126, v64
	v_fmac_f32_e32 v126, v147, v146
	v_fma_f32 v64, -v127, v126, v64
	v_div_scale_f32 v127, s[56:57], v122, v122, v10
	v_rcp_f32_e32 v147, v127
	v_div_fmas_f32 v64, v64, v146, v126
	v_div_fixup_f32 v119, v64, v119, v9
	v_fma_f32 v64, -v127, v147, 1.0
	v_fmac_f32_e32 v147, v64, v147
	v_div_scale_f32 v64, vcc, v10, v122, v10
	v_mul_f32_e32 v126, v64, v147
	v_fma_f32 v146, -v127, v126, v64
	v_fmac_f32_e32 v126, v146, v147
	v_fma_f32 v64, -v127, v126, v64
	v_div_scale_f32 v127, s[56:57], v123, v123, v11
	v_rcp_f32_e32 v150, v127
	v_div_fmas_f32 v64, v64, v147, v126
	v_div_fixup_f32 v146, v64, v122, v10
	v_mul_f32_e32 v147, 0xbfb8aa3b, v26
	v_fma_f32 v64, -v127, v150, 1.0
	v_fmac_f32_e32 v150, v64, v150
	v_div_scale_f32 v64, vcc, v11, v123, v11
	v_mul_f32_e32 v122, v64, v150
	v_fma_f32 v126, -v127, v122, v64
	v_fmac_f32_e32 v122, v126, v150
	v_fma_f32 v64, -v127, v122, v64
	v_mul_f32_e32 v126, 0xbfb8aa3b, v24
	v_mul_f32_e32 v127, 0xbfb8aa3b, v25
	v_exp_f32_e32 v126, v126
	v_exp_f32_e32 v127, v127
	v_exp_f32_e32 v148, v147
	v_mul_f32_e32 v147, 0xbfb8aa3b, v27
	v_div_fmas_f32 v64, v64, v150, v122
	v_add_f32_e32 v126, 1.0, v126
	v_add_f32_e32 v127, 1.0, v127
	v_exp_f32_e32 v149, v147
	v_div_scale_f32 v151, s[56:57], v126, v126, v24
	v_rcp_f32_e32 v203, v151
	v_div_fixup_f32 v147, v64, v123, v11
	v_add_f32_e32 v148, 1.0, v148
	v_add_f32_e32 v149, 1.0, v149
	v_fma_f32 v64, -v151, v203, 1.0
	v_fmac_f32_e32 v203, v64, v203
	v_div_scale_f32 v64, vcc, v24, v126, v24
	v_mul_f32_e32 v122, v64, v203
	v_fma_f32 v123, -v151, v122, v64
	v_fmac_f32_e32 v122, v123, v203
	v_div_scale_f32 v123, s[56:57], v127, v127, v25
	v_rcp_f32_e32 v150, v123
	v_fma_f32 v64, -v151, v122, v64
	v_div_fmas_f32 v64, v64, v203, v122
	v_div_fixup_f32 v122, v64, v126, v24
	v_fma_f32 v64, -v123, v150, 1.0
	v_fmac_f32_e32 v150, v64, v150
	v_div_scale_f32 v64, vcc, v25, v127, v25
	v_mul_f32_e32 v126, v64, v150
	v_fma_f32 v151, -v123, v126, v64
	v_fmac_f32_e32 v126, v151, v150
	v_div_scale_f32 v151, s[56:57], v148, v148, v26
	v_rcp_f32_e32 v203, v151
	v_fma_f32 v64, -v123, v126, v64
	v_div_fmas_f32 v64, v64, v150, v126
	v_div_fixup_f32 v123, v64, v127, v25
	v_fma_f32 v64, -v151, v203, 1.0
	v_fmac_f32_e32 v203, v64, v203
	v_div_scale_f32 v64, vcc, v26, v148, v26
	v_mul_f32_e32 v126, v64, v203
	v_fma_f32 v127, -v151, v126, v64
	v_fmac_f32_e32 v126, v127, v203
	v_div_scale_f32 v127, s[56:57], v149, v149, v27
	v_rcp_f32_e32 v204, v127
	v_fma_f32 v64, -v151, v126, v64
	v_div_fmas_f32 v64, v64, v203, v126
	v_div_fixup_f32 v148, v64, v148, v26
	v_fma_f32 v64, -v127, v204, 1.0
	v_fmac_f32_e32 v204, v64, v204
	v_div_scale_f32 v64, vcc, v27, v149, v27
	v_mul_f32_e32 v203, v64, v204
	v_fma_f32 v126, -v127, v203, v64
	v_fmac_f32_e32 v203, v126, v204
	v_fma_f32 v64, -v127, v203, v64
	v_mul_f32_e32 v126, 0xbfb8aa3b, v28
	v_mul_f32_e32 v127, 0xbfb8aa3b, v29
	v_exp_f32_e32 v126, v126
	v_exp_f32_e32 v127, v127
	v_div_fmas_f32 v64, v64, v204, v203
	v_div_fixup_f32 v149, v64, v149, v27
	v_mul_f32_e32 v150, 0xbfb8aa3b, v30
	v_add_f32_e32 v126, 1.0, v126
	v_add_f32_e32 v127, 1.0, v127
	v_mul_f32_e32 v151, 0xbfb8aa3b, v31
	v_div_scale_f32 v205, s[56:57], v126, v126, v28
	v_rcp_f32_e32 v206, v205
	v_exp_f32_e32 v150, v150
	v_exp_f32_e32 v151, v151
	v_fma_f32 v64, -v205, v206, 1.0
	v_fmac_f32_e32 v206, v64, v206
	v_div_scale_f32 v64, vcc, v28, v126, v28
	v_mul_f32_e32 v203, v64, v206
	v_fma_f32 v204, -v205, v203, v64
	v_fmac_f32_e32 v203, v204, v206
	v_div_scale_f32 v204, s[56:57], v127, v127, v29
	v_fma_f32 v64, -v205, v203, v64
	v_rcp_f32_e32 v205, v204
	v_div_fmas_f32 v64, v64, v206, v203
	v_div_fixup_f32 v126, v64, v126, v28
	v_add_f32_e32 v150, 1.0, v150
	v_add_f32_e32 v151, 1.0, v151
	v_fma_f32 v64, -v204, v205, 1.0
	v_fmac_f32_e32 v205, v64, v205
	v_div_scale_f32 v64, vcc, v29, v127, v29
	v_mul_f32_e32 v203, v64, v205
	v_fma_f32 v206, -v204, v203, v64
	v_fmac_f32_e32 v203, v206, v205
	v_fma_f32 v64, -v204, v203, v64
	v_div_scale_f32 v204, s[56:57], v150, v150, v30
	v_rcp_f32_e32 v206, v204
	v_div_fmas_f32 v64, v64, v205, v203
	v_div_fixup_f32 v127, v64, v127, v29
	v_fma_f32 v64, -v204, v206, 1.0
	v_fmac_f32_e32 v206, v64, v206
	v_div_scale_f32 v64, vcc, v30, v150, v30
	v_mul_f32_e32 v203, v64, v206
	v_fma_f32 v205, -v204, v203, v64
	v_fmac_f32_e32 v203, v205, v206
	v_fma_f32 v64, -v204, v203, v64
	v_div_scale_f32 v204, s[56:57], v151, v151, v31
	v_rcp_f32_e32 v205, v204
	v_div_fmas_f32 v64, v64, v206, v203
	v_div_fixup_f32 v150, v64, v150, v30
	s_lshl_b64 s[56:57], s[0:1], 19
	v_fma_f32 v64, -v204, v205, 1.0
	v_fmac_f32_e32 v205, v64, v205
	v_div_scale_f32 v64, vcc, v31, v151, v31
	s_add_u32 s56, s36, s56
	v_mul_f32_e32 v203, v64, v205
	s_addc_u32 s57, s37, s57
	s_lshl_b32 s38, s4, 7
	v_fma_f32 v206, -v204, v203, v64
	s_lshl_b64 s[4:5], s[38:39], 1
	v_fmac_f32_e32 v203, v206, v205
	s_add_u32 s4, s56, s4
	v_fma_f32 v64, -v204, v203, v64
	s_addc_u32 s5, s57, s5
	v_div_fmas_f32 v64, v64, v205, v203
	s_add_u32 s56, s4, 0xffffe000
	v_div_fixup_f32 v151, v64, v151, v31
	s_addc_u32 s57, s5, -1

.LBB0_437:
	s_andn2_b64 vcc, exec, s[4:5]
	s_mov_b64 s[4:5], 0x1000
	s_cbranch_vccnz .LBB0_443
	s_cmp_lg_u32 s65, 0
	s_cbranch_scc0 .LBB0_447
	s_lshl_b64 s[58:59], s[0:1], 13
	s_cmp_eq_u32 s65, 1
	s_cselect_b64 s[56:57], -1, 0
	s_and_b64 s[0:1], s[56:57], exec
	s_cselect_b32 s1, s43, s45
	s_cselect_b32 s0, s42, s44
	v_mov_b32_e32 v120, v18
	v_mov_b32_e32 v121, v22
	v_mul_f32_e32 v122, v120, v120
	v_mul_f32_e32 v123, v121, v121
	global_load_dword v143, v192, s[0:1]
	global_load_dword v141, v192, s[0:1] offset:64
	global_load_dword v125, v192, s[0:1] offset:128
	global_load_dword v121, v192, s[0:1] offset:192
	global_load_dword v142, v192, s[0:1] offset:256
	global_load_dword v140, v192, s[0:1] offset:320
	v_and_b32_e32 v77, 64, v201
	v_xor_b32_e32 v76, 1, v201
	v_add_u32_e32 v77, 64, v77
	v_cmp_lt_i32_e32 vcc, v76, v77
	v_mov_b32_e32 v82, v41
	v_mov_b32_e32 v83, v45
	v_cndmask_b32_e32 v76, v201, v76, vcc
	v_lshlrev_b32_e32 v146, 2, v76
	v_xor_b32_e32 v76, 2, v201
	v_cmp_lt_i32_e32 vcc, v76, v77
	v_mul_f32_e32 v82, v82, v82
	v_mul_f32_e32 v83, v83, v83
	v_mul_f32_e32 v86, v36, v36
	v_mul_f32_e32 v87, v37, v37
	v_cndmask_b32_e32 v76, v201, v76, vcc
	v_lshlrev_b32_e32 v147, 2, v76
	v_xor_b32_e32 v76, 4, v201
	v_cmp_lt_i32_e32 vcc, v76, v77
	v_mov_b32_e32 v78, v48
	v_mov_b32_e32 v79, v52
	v_cndmask_b32_e32 v76, v201, v76, vcc
	v_lshlrev_b32_e32 v148, 2, v76
	v_xor_b32_e32 v76, 8, v201
	v_cmp_lt_i32_e32 vcc, v76, v77
	v_mov_b32_e32 v77, v44
	v_fma_f32 v86, v32, v32, v86
	v_fma_f32 v87, v33, v33, v87
	v_cndmask_b32_e32 v76, v201, v76, vcc
	v_lshlrev_b32_e32 v149, 2, v76
	v_mov_b32_e32 v76, v40
	v_mul_f32_e32 v76, v76, v76
	v_mul_f32_e32 v77, v77, v77
	v_mov_b32_e32 v88, v49
	v_mov_b32_e32 v89, v53
	v_mov_b32_e32 v126, v82
	v_mov_b32_e32 v127, v76
	v_mul_f32_e32 v78, v78, v78
	v_mul_f32_e32 v79, v79, v79
	v_mul_f32_e32 v88, v88, v88
	v_mul_f32_e32 v89, v89, v89
	v_pk_add_f32 v[86:87], v[86:87], v[126:127] op_sel:[1,0] op_sel_hi:[0,1]
	v_mov_b32_e32 v76, v83
	v_mov_b32_e32 v80, v56
	v_mov_b32_e32 v81, v60
	v_mov_b32_e32 v90, v57
	v_mov_b32_e32 v91, v61
	v_add_f32_e32 v76, v86, v76
	v_add_f32_e32 v77, v87, v77
	v_mov_b32_e32 v82, v88
	v_mov_b32_e32 v83, v78
	v_mul_f32_e32 v80, v80, v80
	v_mul_f32_e32 v81, v81, v81
	v_mul_f32_e32 v90, v90, v90
	v_mul_f32_e32 v91, v91, v91
	v_add_f32_e32 v76, v76, v82
	v_add_f32_e32 v77, v77, v83
	v_mov_b32_e32 v78, v89
	v_add_f32_e32 v76, v76, v78
	v_add_f32_e32 v77, v77, v79
	v_mov_b32_e32 v78, v90
	v_mov_b32_e32 v79, v80
	v_add_f32_e32 v76, v76, v78
	v_add_f32_e32 v77, v77, v79
	v_mov_b32_e32 v80, v91
	v_add_f32_e32 v76, v76, v80
	v_add_f32_e32 v77, v77, v81
	ds_bpermute_b32 v79, v146, v77
	ds_bpermute_b32 v78, v146, v76
	global_load_dword v124, v192, s[0:1] offset:384
	global_load_dword v120, v192, s[0:1] offset:448
	v_mov_b32_e32 v88, v3
	v_mov_b32_e32 v89, v11
	s_waitcnt lgkmcnt(0)
	v_add_f32_e32 v76, v76, v78
	v_add_f32_e32 v77, v77, v79
	ds_bpermute_b32 v79, v147, v77
	ds_bpermute_b32 v78, v147, v76
	v_mov_b32_e32 v92, v42
	v_mov_b32_e32 v93, v46
	v_mov_b32_e32 v98, v43
	v_mov_b32_e32 v99, v47
	s_waitcnt lgkmcnt(0)
	v_add_f32_e32 v76, v76, v78
	v_add_f32_e32 v77, v77, v79
	ds_bpermute_b32 v79, v148, v77
	ds_bpermute_b32 v78, v148, v76
	v_mul_f32_e32 v90, v88, v88
	v_mul_f32_e32 v91, v89, v89
	v_mov_b32_e32 v88, v27
	v_mov_b32_e32 v89, v31
	v_mul_f32_e32 v84, v38, v38
	v_mul_f32_e32 v85, v39, v39
	s_waitcnt lgkmcnt(0)
	v_add_f32_e32 v76, v76, v78
	v_add_f32_e32 v77, v77, v79
	ds_bpermute_b32 v79, v149, v77
	ds_bpermute_b32 v78, v149, v76
	v_mul_f32_e32 v92, v92, v92
	v_mul_f32_e32 v93, v93, v93
	v_mul_f32_e32 v98, v98, v98
	v_mul_f32_e32 v99, v99, v99
	v_fma_f32 v84, v34, v34, v84
	v_fma_f32 v85, v35, v35, v85
	v_mov_b32_e32 v94, v50
	s_waitcnt lgkmcnt(0)
	v_add_f32_e32 v76, v76, v78
	v_add_f32_e32 v77, v77, v79
	v_mov_b64_e32 v[78:79], s[52:53]
	v_fma_f32 v76, v76, s46, v78
	v_fma_f32 v77, v77, s46, v78
	v_mov_b32_e32 v95, v54
	v_mul_f32_e32 v126, 0x4b800000, v77
	v_cmp_gt_f32_e32 vcc, s60, v77
	v_cmp_gt_f32_e64 s[0:1], s60, v76
	v_mov_b32_e32 v100, v51
	v_cndmask_b32_e32 v77, v77, v126, vcc
	v_rsq_f32_e32 v126, v77
	v_mul_f32_e32 v77, 0x4b800000, v76
	v_cndmask_b32_e64 v76, v76, v77, s[0:1]
	v_rsq_f32_e32 v127, v76
	v_mul_f32_e32 v76, v88, v88
	v_mul_f32_e32 v77, v89, v89
	v_mul_f32_e32 v88, 0x45800000, v126
	v_mov_b32_e32 v101, v55
	v_cndmask_b32_e32 v126, v126, v88, vcc
	v_mov_b32_e32 v88, v98
	v_mov_b32_e32 v89, v92
	v_mul_f32_e32 v94, v94, v94
	v_mul_f32_e32 v95, v95, v95
	v_mul_f32_e32 v100, v100, v100
	v_mul_f32_e32 v101, v101, v101
	v_pk_add_f32 v[84:85], v[84:85], v[88:89] op_sel:[1,0] op_sel_hi:[0,1]
	v_mov_b32_e32 v92, v99
	v_mov_b32_e32 v96, v58
	v_mov_b32_e32 v97, v62
	v_mov_b32_e32 v102, v59
	v_mov_b32_e32 v103, v63
	v_add_f32_e32 v84, v84, v92
	v_add_f32_e32 v85, v85, v93
	v_mov_b32_e32 v88, v100
	v_mov_b32_e32 v89, v94
	v_mul_f32_e32 v96, v96, v96
	v_mul_f32_e32 v97, v97, v97
	v_mul_f32_e32 v102, v102, v102
	v_mul_f32_e32 v103, v103, v103
	v_add_f32_e32 v84, v84, v88
	v_add_f32_e32 v85, v85, v89
	v_mov_b32_e32 v94, v101
	v_add_f32_e32 v84, v84, v94
	v_add_f32_e32 v85, v85, v95
	v_mov_b32_e32 v88, v102
	v_mov_b32_e32 v89, v96
	v_add_f32_e32 v84, v84, v88
	v_add_f32_e32 v85, v85, v89
	v_mov_b32_e32 v96, v103
	v_add_f32_e32 v84, v84, v96
	v_add_f32_e32 v85, v85, v97
	ds_bpermute_b32 v89, v146, v85
	ds_bpermute_b32 v88, v146, v84
	v_mul_f32_e32 v144, 0x45800000, v127
	v_mov_b32_e32 v104, v16
	v_mov_b32_e32 v105, v20
	v_mov_b32_e32 v110, v17
	s_waitcnt lgkmcnt(0)
	v_add_f32_e32 v84, v84, v88
	v_add_f32_e32 v85, v85, v89
	ds_bpermute_b32 v89, v147, v85
	ds_bpermute_b32 v88, v147, v84
	v_mov_b32_e32 v111, v21
	v_cndmask_b32_e64 v96, v127, v144, s[0:1]
	v_mul_f32_e32 v104, v104, v104
	v_mul_f32_e32 v105, v105, v105
	v_mul_f32_e32 v110, v110, v110
	v_mul_f32_e32 v111, v111, v111
	v_mul_f32_e32 v114, v12, v12
	v_mul_f32_e32 v115, v13, v13
	s_waitcnt vmcnt(0)
	v_mul_f32_e32 v92, v96, v143
	v_mov_b32_e32 v106, v0
	v_mov_b32_e32 v107, v8
	v_fma_f32 v114, v4, v4, v114
	v_fma_f32 v115, v5, v5, v115
	v_mov_b32_e32 v116, v1
	v_mov_b32_e32 v117, v9
	v_mul_f32_e32 v127, v33, v92
	s_waitcnt lgkmcnt(0)
	v_add_f32_e32 v84, v84, v88
	v_add_f32_e32 v85, v85, v89
	v_mov_b32_e32 v92, v110
	v_mov_b32_e32 v93, v104
	v_mul_f32_e32 v106, v106, v106
	v_mul_f32_e32 v107, v107, v107
	v_mul_f32_e32 v116, v116, v116
	v_mul_f32_e32 v117, v117, v117
	ds_bpermute_b32 v89, v148, v85
	ds_bpermute_b32 v88, v148, v84
	v_add_f32_e32 v92, v115, v92
	v_add_f32_e32 v93, v114, v93
	v_mov_b32_e32 v104, v111
	v_mov_b32_e32 v108, v24
	v_mov_b32_e32 v109, v28
	v_mov_b32_e32 v118, v25
	v_mov_b32_e32 v119, v29
	v_add_f32_e32 v92, v92, v104
	v_add_f32_e32 v93, v93, v105
	v_mov_b32_e32 v94, v116
	v_mov_b32_e32 v95, v106
	v_mul_f32_e32 v108, v108, v108
	v_mul_f32_e32 v109, v109, v109
	v_mul_f32_e32 v118, v118, v118
	v_mul_f32_e32 v119, v119, v119
	v_add_f32_e32 v92, v92, v94
	v_add_f32_e32 v93, v93, v95
	v_mov_b32_e32 v106, v117
	v_add_f32_e32 v92, v92, v106
	v_add_f32_e32 v93, v93, v107
	v_mov_b32_e32 v94, v118
	v_mov_b32_e32 v95, v108
	v_add_f32_e32 v92, v92, v94
	v_add_f32_e32 v93, v93, v95
	v_mov_b32_e32 v108, v119
	s_waitcnt lgkmcnt(0)
	v_add_f32_e32 v84, v84, v88
	v_add_f32_e32 v85, v85, v89
	v_add_f32_e32 v92, v92, v108
	v_add_f32_e32 v93, v93, v109
	ds_bpermute_b32 v89, v149, v85
	ds_bpermute_b32 v88, v149, v84
	ds_bpermute_b32 v95, v146, v93
	ds_bpermute_b32 v94, v146, v92
	v_mul_f32_e32 v33, v96, v141
	v_mul_f32_e32 v150, v37, v33
	s_waitcnt lgkmcnt(2)
	v_add_f32_e32 v84, v84, v88
	v_add_f32_e32 v85, v85, v89
	v_mul_f32_e32 v33, v96, v125
	s_waitcnt lgkmcnt(0)
	v_add_f32_e32 v88, v92, v94
	v_add_f32_e32 v89, v93, v95
	ds_bpermute_b32 v93, v147, v89
	ds_bpermute_b32 v92, v147, v88
	v_fma_f32 v84, v84, s46, v78
	v_fma_f32 v85, v85, s46, v78
	v_mul_f32_e32 v151, v41, v33
	v_mul_f32_e32 v37, 0x4b800000, v85
	v_cmp_gt_f32_e32 vcc, s60, v85
	s_waitcnt lgkmcnt(0)
	v_add_f32_e32 v88, v88, v92
	v_add_f32_e32 v89, v89, v93
	ds_bpermute_b32 v93, v148, v89
	ds_bpermute_b32 v92, v148, v88
	v_mul_f32_e32 v41, 0x4b800000, v84
	v_cmp_gt_f32_e64 s[0:1], s60, v84
	v_cndmask_b32_e32 v37, v85, v37, vcc
	v_mul_f32_e32 v33, v96, v121
	s_waitcnt lgkmcnt(0)
	v_add_f32_e32 v88, v88, v92
	v_add_f32_e32 v89, v89, v93
	ds_bpermute_b32 v93, v149, v89
	ds_bpermute_b32 v92, v149, v88
	v_cndmask_b32_e64 v41, v84, v41, s[0:1]
	v_mul_f32_e32 v203, v45, v33
	v_mul_f32_e32 v33, v96, v142
	v_rsq_f32_e32 v37, v37
	s_waitcnt lgkmcnt(0)
	v_add_f32_e32 v84, v88, v92
	v_add_f32_e32 v85, v89, v93
	v_mul_f32_e32 v204, v49, v33
	v_fma_f32 v84, v84, s46, v78
	v_fma_f32 v85, v85, s46, v78
	v_mul_f32_e32 v33, v96, v140
	v_mul_f32_e32 v45, 0x4b800000, v85
	v_cmp_gt_f32_e64 s[4:5], s60, v85
	v_rsq_f32_e32 v41, v41
	v_mul_f32_e32 v104, v53, v33
	v_cndmask_b32_e64 v45, v85, v45, s[4:5]
	v_mul_f32_e32 v33, v96, v124
	v_rsq_f32_e32 v45, v45
	v_mul_f32_e32 v105, v57, v33
	v_mul_f32_e32 v33, v96, v120
	v_mul_f32_e32 v106, v61, v33
	v_mul_f32_e32 v33, 0x45800000, v37
	v_cndmask_b32_e32 v92, v37, v33, vcc
	v_mul_f32_e32 v33, 0x45800000, v41
	v_cndmask_b32_e64 v88, v41, v33, s[0:1]
	v_mul_f32_e32 v33, 0x45800000, v45
	v_cndmask_b32_e64 v108, v45, v33, s[4:5]
	v_mul_f32_e32 v33, 0x4b800000, v84
	v_cmp_gt_f32_e32 vcc, s60, v84
	v_mov_b32_e32 v86, v19
	v_mov_b32_e32 v87, v23
	v_cndmask_b32_e32 v33, v84, v33, vcc
	v_lshl_add_u64 v[84:85], s[58:59], 0, v[72:73]
	v_lshlrev_b64 v[144:145], 2, v[84:85]
	v_lshl_add_u64 v[84:85], s[6:7], 0, v[144:145]
	v_lshl_add_u64 v[94:95], s[8:9], 0, v[144:145]
	global_load_dword v85, v[84:85], off
	s_nop 0
	global_load_dword v84, v[94:95], off
	v_or_b32_e32 v94, 64, v144
	v_mov_b32_e32 v95, v145
	v_lshl_add_u64 v[96:97], s[6:7], 0, v[94:95]
	v_lshl_add_u64 v[94:95], s[8:9], 0, v[94:95]
	global_load_dword v97, v[96:97], off
	s_nop 0
	global_load_dword v96, v[94:95], off
	v_or_b32_e32 v98, 0x80, v144
	v_mov_b32_e32 v99, v145
	v_lshl_add_u64 v[100:101], s[6:7], 0, v[98:99]
	v_lshl_add_u64 v[98:99], s[8:9], 0, v[98:99]
	global_load_dword v101, v[100:101], off
	s_nop 0
	global_load_dword v100, v[98:99], off
	v_or_b32_e32 v98, 0xc0, v144
	v_mov_b32_e32 v99, v145
	v_lshl_add_u64 v[102:103], s[6:7], 0, v[98:99]
	v_lshl_add_u64 v[98:99], s[8:9], 0, v[98:99]
	global_load_dword v103, v[102:103], off
	s_nop 0
	global_load_dword v102, v[98:99], off
	v_mul_f32_e32 v112, v14, v14
	v_mul_f32_e32 v113, v15, v15
	v_mul_f32_e32 v86, v86, v86
	v_mul_f32_e32 v87, v87, v87
	v_fma_f32 v112, v6, v6, v112
	v_fma_f32 v113, v7, v7, v113
	v_mov_b32_e32 v80, v2
	v_mov_b32_e32 v81, v10
	v_mov_b32_e32 v94, v86
	v_mov_b32_e32 v95, v122
	v_mul_f32_e32 v80, v80, v80
	v_mul_f32_e32 v81, v81, v81
	v_add_f32_e32 v94, v113, v94
	v_add_f32_e32 v95, v112, v95
	v_mov_b32_e32 v122, v87
	v_mov_b32_e32 v82, v26
	v_mov_b32_e32 v83, v30
	v_add_f32_e32 v86, v94, v122
	v_add_f32_e32 v87, v95, v123
	v_mov_b32_e32 v94, v90
	v_mov_b32_e32 v95, v80
	v_mul_f32_e32 v82, v82, v82
	v_mul_f32_e32 v83, v83, v83
	v_add_f32_e32 v86, v86, v94
	v_add_f32_e32 v87, v87, v95
	v_mov_b32_e32 v80, v91
	v_add_f32_e32 v80, v86, v80
	v_add_f32_e32 v81, v87, v81
	v_mov_b32_e32 v86, v76
	v_mov_b32_e32 v87, v82
	v_add_f32_e32 v80, v80, v86
	v_add_f32_e32 v81, v81, v87
	v_mov_b32_e32 v82, v77
	v_add_f32_e32 v76, v80, v82
	v_add_f32_e32 v77, v81, v83
	ds_bpermute_b32 v81, v146, v77
	ds_bpermute_b32 v80, v146, v76
	v_rsq_f32_e32 v33, v33
	v_mov_b32_e32 v49, v32
	v_mov_b32_e32 v53, v36
	v_mov_b32_e32 v57, v40
	s_waitcnt lgkmcnt(0)
	v_add_f32_e32 v76, v76, v80
	v_add_f32_e32 v77, v77, v81
	ds_bpermute_b32 v81, v147, v77
	ds_bpermute_b32 v80, v147, v76
	v_mul_f32_e32 v37, 0x45800000, v33
	v_cndmask_b32_e32 v33, v33, v37, vcc
	v_mul_f32_e32 v37, v33, v143
	v_mul_f32_e32 v41, v5, v37
	s_waitcnt lgkmcnt(0)
	v_add_f32_e32 v76, v76, v80
	v_add_f32_e32 v77, v77, v81
	ds_bpermute_b32 v81, v148, v77
	ds_bpermute_b32 v80, v148, v76
	v_mul_f32_e32 v5, v33, v141
	v_mul_f32_e32 v45, v13, v5
	v_mul_f32_e32 v5, v33, v125
	v_mul_f32_e32 v5, v17, v5
	s_waitcnt lgkmcnt(0)
	v_add_f32_e32 v76, v76, v80
	v_add_f32_e32 v77, v77, v81
	ds_bpermute_b32 v81, v149, v77
	ds_bpermute_b32 v80, v149, v76
	v_mul_f32_e32 v13, v33, v121
	v_mul_f32_e32 v17, v33, v142
	v_mul_f32_e32 v13, v21, v13
	v_mul_f32_e32 v21, v1, v17
	v_mul_f32_e32 v1, v33, v140
	s_waitcnt lgkmcnt(0)
	v_add_f32_e32 v76, v76, v80
	v_add_f32_e32 v77, v77, v81
	v_mul_f32_e32 v109, v9, v1
	v_mul_f32_e32 v1, v33, v124
	v_fma_f32 v76, v76, s46, v78
	v_fma_f32 v77, v77, s46, v78
	v_mul_f32_e32 v17, v25, v1
	v_mul_f32_e32 v9, 0x4b800000, v77
	v_cmp_gt_f32_e32 vcc, s60, v77
	v_mul_f32_e32 v25, 0x4b800000, v76
	v_cmp_gt_f32_e64 s[0:1], s60, v76
	v_cndmask_b32_e32 v9, v77, v9, vcc
	v_mul_f32_e32 v1, v33, v120
	v_cndmask_b32_e64 v25, v76, v25, s[0:1]
	v_mul_f32_e32 v76, v126, v142
	v_mul_f32_e32 v77, v126, v143
	v_mul_f32_e32 v32, v48, v76
	v_mul_f32_e32 v33, v49, v77
	s_waitcnt vmcnt(7)
	v_mov_b32_e32 v76, v85
	s_waitcnt vmcnt(6)
	v_mov_b32_e32 v77, v84
	v_rsq_f32_e32 v9, v9
	v_mul_f32_e32 v48, v32, v84
	v_mul_f32_e32 v49, v33, v85
	v_mul_f32_e32 v32, v32, v76
	v_mul_f32_e32 v33, v33, v77
	v_mul_f32_e32 v76, v126, v140
	v_mul_f32_e32 v77, v126, v141
	v_rsq_f32_e32 v25, v25
	v_mul_f32_e32 v36, v52, v76
	v_mul_f32_e32 v37, v53, v77
	s_waitcnt vmcnt(5)
	v_mov_b32_e32 v76, v97
	s_waitcnt vmcnt(4)
	v_mov_b32_e32 v77, v96
	v_mul_f32_e32 v52, v36, v96
	v_mul_f32_e32 v53, v37, v97
	v_mul_f32_e32 v36, v36, v76
	v_mul_f32_e32 v37, v37, v77
	v_mul_f32_e32 v76, v126, v124
	v_mul_f32_e32 v77, v126, v125
	v_mul_f32_e32 v56, v56, v76
	v_mul_f32_e32 v57, v57, v77
	s_waitcnt vmcnt(3)
	v_mov_b32_e32 v78, v101
	s_waitcnt vmcnt(2)
	v_mov_b32_e32 v79, v100
	v_mul_f32_e32 v110, v29, v1
	v_mul_f32_e32 v1, 0x45800000, v9
	v_mul_f32_e32 v76, v56, v100
	v_mul_f32_e32 v77, v57, v101
	v_mul_f32_e32 v56, v56, v78
	v_mul_f32_e32 v57, v57, v79
	v_mul_f32_e32 v78, v126, v120
	v_mul_f32_e32 v79, v126, v121
	v_mov_b32_e32 v61, v44
	v_cndmask_b32_e32 v148, v9, v1, vcc
	v_mul_f32_e32 v1, 0x45800000, v25
	v_mul_f32_e32 v60, v60, v78
	v_mul_f32_e32 v61, v61, v79
	v_cndmask_b32_e64 v146, v25, v1, s[0:1]
	s_waitcnt vmcnt(0)
	v_mul_f32_e32 v78, v60, v102
	v_mul_f32_e32 v79, v61, v103
	v_mov_b32_e32 v80, v103
	v_mov_b32_e32 v81, v102
	v_cndmask_b32_e64 v64, v202, 1.0, s[56:57]
	v_mul_f32_e32 v60, v60, v80
	v_mul_f32_e32 v61, v61, v81
	v_or_b32_e32 v80, 0x100, v144
	v_mov_b32_e32 v81, v145
	v_lshl_add_u64 v[82:83], s[6:7], 0, v[80:81]
	v_lshl_add_u64 v[80:81], s[8:9], 0, v[80:81]
	global_load_dword v1, v[82:83], off
	global_load_dword v9, v[80:81], off
	v_or_b32_e32 v80, 0x140, v144
	v_mov_b32_e32 v81, v145
	v_lshl_add_u64 v[82:83], s[6:7], 0, v[80:81]
	v_lshl_add_u64 v[80:81], s[8:9], 0, v[80:81]
	v_or_b32_e32 v84, 0x180, v144
	v_mov_b32_e32 v85, v145
	v_lshl_add_u64 v[86:87], s[6:7], 0, v[84:85]
	v_lshl_add_u64 v[84:85], s[8:9], 0, v[84:85]
	global_load_dword v25, v[82:83], off
	global_load_dword v29, v[80:81], off
	global_load_dword v40, v[86:87], off
	global_load_dword v44, v[84:85], off
	v_or_b32_e32 v80, 0x1c0, v144
	v_mov_b32_e32 v81, v145
	v_lshl_add_u64 v[82:83], s[6:7], 0, v[80:81]
	v_lshl_add_u64 v[80:81], s[8:9], 0, v[80:81]
	global_load_dword v89, v[82:83], off
	global_load_dword v93, v[80:81], off
	v_mov_b32_e32 v82, v33
	v_mov_b32_e32 v84, v37
	v_mov_b32_e32 v80, v49
	v_mov_b32_e32 v86, v53
	v_mov_b32_e32 v90, v77
	v_mov_b32_e32 v94, v57
	v_mov_b32_e32 v96, v79
	v_mov_b32_e32 v98, v61
	s_waitcnt vmcnt(7)
	v_mul_f32_e32 v33, v204, v1
	s_waitcnt vmcnt(6)
	v_mul_f32_e32 v83, v127, v9
	v_mul_f32_e32 v81, v127, v1
	v_mul_f32_e32 v49, v204, v9
	v_add_f32_e32 v32, v32, v82
	v_add_f32_e32 v33, v33, v83
	v_add_f32_e64 v48, v80, -v48
	v_add_f32_e64 v49, v81, -v49
	s_waitcnt vmcnt(5)
	v_mul_f32_e32 v37, v104, v25
	s_waitcnt vmcnt(4)
	v_mul_f32_e32 v85, v150, v29
	v_mul_f32_e32 v87, v150, v25
	v_mul_f32_e32 v53, v104, v29
	s_waitcnt vmcnt(3)
	v_mul_f32_e32 v91, v151, v40
	s_waitcnt vmcnt(2)
	v_mul_f32_e32 v77, v105, v44
	v_mul_f32_e32 v95, v151, v44
	v_mul_f32_e32 v57, v105, v40
	s_waitcnt vmcnt(1)
	v_mul_f32_e32 v97, v203, v89
	s_waitcnt vmcnt(0)
	v_mul_f32_e32 v79, v106, v93
	v_mul_f32_e32 v99, v203, v93
	v_mul_f32_e32 v61, v106, v89
	v_add_f32_e32 v36, v36, v84
	v_add_f32_e32 v37, v37, v85
	v_add_f32_e32 v56, v56, v94
	v_add_f32_e32 v57, v57, v95
	v_add_f32_e32 v60, v60, v98
	v_add_f32_e32 v61, v61, v99
	v_mul_f32_e32 v84, v64, v32
	v_mul_f32_e32 v85, v64, v33
	v_add_f32_e64 v32, v86, -v52
	v_add_f32_e64 v33, v87, -v53
	v_mul_f32_e32 v86, v64, v36
	v_mul_f32_e32 v87, v64, v37
	v_add_f32_e64 v36, v90, -v76
	v_add_f32_e64 v37, v91, -v77
	v_add_f32_e64 v52, v96, -v78
	v_add_f32_e64 v53, v97, -v79
	v_mul_f32_e32 v90, v64, v56
	v_mul_f32_e32 v91, v64, v57
	v_mul_f32_e32 v76, v64, v48
	v_mul_f32_e32 v77, v64, v49
	v_mul_f32_e32 v78, v64, v32
	v_mul_f32_e32 v79, v64, v33
	v_mul_f32_e32 v80, v64, v36
	v_mul_f32_e32 v81, v64, v37
	v_mul_f32_e32 v82, v64, v52
	v_mul_f32_e32 v83, v64, v53
	v_mul_f32_e32 v94, v64, v60
	v_mul_f32_e32 v95, v64, v61
	v_or_b32_e32 v32, 0x200, v144
	v_mov_b32_e32 v33, v145
	v_or_b32_e32 v48, 0x240, v144
	v_mov_b32_e32 v49, v145
	v_lshl_add_u64 v[36:37], s[6:7], 0, v[32:33]
	v_lshl_add_u64 v[32:33], s[8:9], 0, v[32:33]
	v_lshl_add_u64 v[52:53], s[6:7], 0, v[48:49]
	v_lshl_add_u64 v[48:49], s[8:9], 0, v[48:49]
	v_or_b32_e32 v56, 0x280, v144
	v_mov_b32_e32 v57, v145
	v_lshl_add_u64 v[60:61], s[6:7], 0, v[56:57]
	v_lshl_add_u64 v[56:57], s[8:9], 0, v[56:57]
	global_load_dword v37, v[36:37], off
	s_nop 0
	global_load_dword v36, v[32:33], off
	s_nop 0
	global_load_dword v33, v[52:53], off
	global_load_dword v32, v[48:49], off
	s_nop 0
	global_load_dword v49, v[60:61], off
	global_load_dword v48, v[56:57], off
	v_or_b32_e32 v52, 0x2c0, v144
	v_mov_b32_e32 v53, v145
	v_lshl_add_u64 v[56:57], s[6:7], 0, v[52:53]
	v_lshl_add_u64 v[52:53], s[8:9], 0, v[52:53]
	global_load_dword v57, v[56:57], off
	s_nop 0
	global_load_dword v56, v[52:53], off
	v_mul_f32_e32 v52, v92, v142
	v_mul_f32_e32 v53, v92, v143
	v_mov_b32_e32 v60, v50
	v_mov_b32_e32 v61, v34
	v_mul_f32_e32 v96, v92, v140
	v_mul_f32_e32 v97, v92, v141
	v_mov_b32_e32 v98, v54
	v_mov_b32_e32 v99, v38
	v_mul_f32_e32 v100, v92, v124
	v_mul_f32_e32 v101, v92, v125
	v_mov_b32_e32 v102, v58
	v_mov_b32_e32 v103, v42
	v_mul_f32_e32 v93, v92, v121
	v_mul_f32_e32 v92, v92, v120
	v_mov_b32_e32 v104, v62
	v_mov_b32_e32 v105, v46
	v_mul_f32_e32 v52, v60, v52
	v_mul_f32_e32 v53, v61, v53
	v_mul_f32_e32 v60, v98, v96
	v_mul_f32_e32 v61, v99, v97
	v_mul_f32_e32 v96, v102, v100
	v_mul_f32_e32 v97, v103, v101
	v_mul_f32_e32 v92, v104, v92
	v_mul_f32_e32 v93, v105, v93
	s_waitcnt vmcnt(7)
	v_mov_b32_e32 v100, v37
	s_waitcnt vmcnt(6)
	v_mul_f32_e32 v98, v52, v36
	v_mul_f32_e32 v99, v53, v37
	v_mov_b32_e32 v101, v36
	s_waitcnt vmcnt(4)
	v_mul_f32_e32 v102, v60, v32
	v_mul_f32_e32 v103, v61, v33
	v_mov_b32_e32 v36, v33
	v_mov_b32_e32 v37, v32
	s_waitcnt vmcnt(2)
	v_mul_f32_e32 v104, v96, v48
	v_mul_f32_e32 v105, v97, v49
	v_mov_b32_e32 v32, v49
	v_mov_b32_e32 v33, v48
	s_waitcnt vmcnt(1)
	v_mov_b32_e32 v106, v57
	s_waitcnt vmcnt(0)
	v_mov_b32_e32 v107, v56
	v_mul_f32_e32 v106, v92, v106
	v_mul_f32_e32 v107, v93, v107
	v_mul_f32_e32 v48, v92, v56
	v_mul_f32_e32 v49, v93, v57
	v_mul_f32_e32 v52, v52, v100
	v_mul_f32_e32 v53, v53, v101
	v_mul_f32_e32 v56, v60, v36
	v_mul_f32_e32 v57, v61, v37
	v_mul_f32_e32 v60, v96, v32
	v_mul_f32_e32 v61, v97, v33
	v_or_b32_e32 v32, 0x300, v144
	v_mov_b32_e32 v33, v145
	v_or_b32_e32 v92, 0x340, v144
	v_mov_b32_e32 v93, v145
	v_lshl_add_u64 v[36:37], s[6:7], 0, v[32:33]
	v_lshl_add_u64 v[96:97], s[6:7], 0, v[92:93]
	v_lshl_add_u64 v[92:93], s[8:9], 0, v[92:93]
	v_or_b32_e32 v100, 0x380, v144
	v_mov_b32_e32 v101, v145
	v_lshl_add_u64 v[32:33], s[8:9], 0, v[32:33]
	v_lshl_add_u64 v[112:113], s[6:7], 0, v[100:101]
	v_lshl_add_u64 v[100:101], s[8:9], 0, v[100:101]
	global_load_dword v114, v[36:37], off
	global_load_dword v115, v[32:33], off
	s_nop 0
	global_load_dword v96, v[96:97], off
	s_nop 0
	global_load_dword v97, v[92:93], off
	s_nop 0
	global_load_dword v92, v[112:113], off
	global_load_dword v93, v[100:101], off
	v_or_b32_e32 v32, 0x3c0, v144
	v_mov_b32_e32 v33, v145
	v_lshl_add_u64 v[36:37], s[6:7], 0, v[32:33]
	v_lshl_add_u64 v[32:33], s[8:9], 0, v[32:33]
	global_load_dword v112, v[36:37], off
	global_load_dword v113, v[32:33], off
	v_mov_b32_e32 v32, v143
	v_mov_b32_e32 v33, v142
	v_mov_b32_e32 v50, v35
	v_mov_b32_e32 v34, v141
	v_mov_b32_e32 v35, v140
	v_mov_b32_e32 v54, v39
	v_mov_b32_e32 v36, v125
	v_mov_b32_e32 v37, v124
	v_mov_b32_e32 v38, v121
	v_mov_b32_e32 v39, v120
	v_mul_f32_e32 v116, v88, v32
	v_mul_f32_e32 v117, v88, v33
	v_mov_b32_e32 v58, v43
	v_mov_b32_e32 v62, v47
	v_mul_f32_e32 v118, v88, v34
	v_mul_f32_e32 v119, v88, v35
	v_mul_f32_e32 v122, v88, v36
	v_mul_f32_e32 v123, v88, v37
	v_mul_f32_e32 v89, v88, v39
	v_mul_f32_e32 v88, v88, v38
	v_mul_f32_e32 v50, v50, v116
	v_mul_f32_e32 v51, v51, v117
	v_mul_f32_e32 v54, v54, v118
	v_mul_f32_e32 v55, v55, v119
	v_mul_f32_e32 v58, v58, v122
	v_mul_f32_e32 v59, v59, v123
	v_mul_f32_e32 v62, v62, v88
	v_mul_f32_e32 v63, v63, v89
	v_mov_b32_e32 v42, v52
	v_mov_b32_e32 v100, v60
	v_mov_b32_e32 v46, v56
	s_waitcnt vmcnt(7)
	v_mov_b32_e32 v117, v114
	s_waitcnt vmcnt(6)
	v_mov_b32_e32 v116, v115
	v_mul_f32_e32 v88, v50, v114
	v_mul_f32_e32 v89, v51, v115
	v_mul_f32_e32 v50, v50, v116
	v_mul_f32_e32 v51, v51, v117
	s_waitcnt vmcnt(3)
	v_mov_b32_e32 v123, v92
	s_waitcnt vmcnt(2)
	v_mov_b32_e32 v122, v93
	v_mul_f32_e32 v114, v54, v96
	v_mul_f32_e32 v115, v55, v97
	v_mov_b32_e32 v118, v97
	v_mov_b32_e32 v119, v96
	v_mul_f32_e32 v96, v58, v92
	v_mul_f32_e32 v97, v59, v93
	v_mul_f32_e32 v58, v58, v122
	v_mul_f32_e32 v59, v59, v123
	v_mov_b32_e32 v43, v51
	v_pk_mov_b32 v[50:51], v[52:53], v[50:51] op_sel:[1,0]
	v_mul_f32_e32 v54, v54, v118
	v_mul_f32_e32 v55, v55, v119
	v_mov_b32_e32 v101, v59
	v_pk_mov_b32 v[58:59], v[60:61], v[58:59] op_sel:[1,0]
	v_add_f32_e32 v42, v42, v50
	v_add_f32_e32 v43, v43, v51
	v_mov_b32_e32 v47, v55
	v_pk_mov_b32 v[54:55], v[56:57], v[54:55] op_sel:[1,0]
	v_add_f32_e32 v50, v100, v58
	v_add_f32_e32 v51, v101, v59
	v_mul_f32_e32 v100, v64, v42
	v_mul_f32_e32 v101, v64, v43
	s_waitcnt vmcnt(0)
	v_mov_b32_e32 v42, v113
	v_mov_b32_e32 v43, v112
	v_mul_f32_e32 v92, v62, v112
	v_mul_f32_e32 v93, v63, v113
	v_pk_mov_b32 v[126:127], v[98:99], v[88:89] op_sel:[1,0]
	v_mov_b32_e32 v99, v89
	v_pk_mov_b32 v[88:89], v[102:103], v[114:115] op_sel:[1,0]
	v_mov_b32_e32 v103, v115
	v_add_f32_e32 v46, v46, v54
	v_add_f32_e32 v47, v47, v55
	v_mul_f32_e32 v42, v62, v42
	v_mul_f32_e32 v43, v63, v43
	v_pk_mov_b32 v[114:115], v[104:105], v[96:97] op_sel:[1,0]
	v_mov_b32_e32 v105, v97
	v_pk_mov_b32 v[96:97], v[48:49], v[92:93] op_sel:[1,0]
	v_mov_b32_e32 v49, v93
	v_add_f32_e64 v52, v88, -v102
	v_add_f32_e64 v53, v89, -v103
	v_mul_f32_e32 v102, v64, v46
	v_mul_f32_e32 v103, v64, v47
	v_mov_b32_e32 v46, v106
	v_mov_b32_e32 v47, v43
	v_pk_mov_b32 v[42:43], v[106:107], v[42:43] op_sel:[1,0]
	v_add_f32_e64 v92, v126, -v98
	v_add_f32_e64 v93, v127, -v99
	v_add_f32_e64 v56, v114, -v104
	v_add_f32_e64 v57, v115, -v105
	v_add_f32_e64 v48, v96, -v48
	v_add_f32_e64 v49, v97, -v49
	v_add_f32_e32 v42, v46, v42
	v_add_f32_e32 v43, v47, v43
	v_mul_f32_e32 v88, v64, v92
	v_mul_f32_e32 v89, v64, v93
	v_mul_f32_e32 v92, v64, v52
	v_mul_f32_e32 v93, v64, v53
	v_mul_f32_e32 v96, v64, v56
	v_mul_f32_e32 v97, v64, v57
	v_mul_f32_e32 v104, v64, v50
	v_mul_f32_e32 v105, v64, v51
	v_mul_f32_e32 v98, v64, v48
	v_mul_f32_e32 v99, v64, v49
	v_mul_f32_e32 v106, v64, v42
	v_mul_f32_e32 v107, v64, v43
	v_or_b32_e32 v42, 0x1000, v144
	v_mov_b32_e32 v43, v145
	v_or_b32_e32 v48, 0x1040, v144
	v_mov_b32_e32 v49, v145
	v_lshl_add_u64 v[46:47], s[6:7], 0, v[42:43]
	v_lshl_add_u64 v[42:43], s[8:9], 0, v[42:43]
	v_lshl_add_u64 v[50:51], s[6:7], 0, v[48:49]
	v_lshl_add_u64 v[48:49], s[8:9], 0, v[48:49]
	v_or_b32_e32 v52, 0x1080, v144
	v_mov_b32_e32 v53, v145
	v_lshl_add_u64 v[54:55], s[6:7], 0, v[52:53]
	v_lshl_add_u64 v[52:53], s[8:9], 0, v[52:53]
	global_load_dword v47, v[46:47], off
	s_nop 0
	global_load_dword v46, v[42:43], off
	s_nop 0
	global_load_dword v43, v[50:51], off
	global_load_dword v42, v[48:49], off
	s_nop 0
	global_load_dword v49, v[54:55], off
	global_load_dword v48, v[52:53], off
	v_or_b32_e32 v50, 0x10c0, v144
	v_mov_b32_e32 v51, v145
	v_lshl_add_u64 v[52:53], s[6:7], 0, v[50:51]
	v_lshl_add_u64 v[50:51], s[8:9], 0, v[50:51]
	global_load_dword v53, v[52:53], off
	s_nop 0
	global_load_dword v52, v[50:51], off
	v_mul_f32_e32 v50, v108, v142
	v_mul_f32_e32 v51, v108, v143
	v_mov_b32_e32 v1, v4
	v_mul_f32_e32 v54, v108, v140
	v_mul_f32_e32 v55, v108, v141
	v_mov_b32_e32 v9, v12
	v_mul_f32_e32 v56, v108, v124
	v_mul_f32_e32 v57, v108, v125
	v_mov_b32_e32 v25, v16
	v_mul_f32_e32 v58, v108, v120
	v_mul_f32_e32 v59, v108, v121
	v_mov_b32_e32 v29, v20
	v_mul_f32_e32 v0, v0, v50
	v_mul_f32_e32 v1, v1, v51
	v_mul_f32_e32 v8, v8, v54
	v_mul_f32_e32 v9, v9, v55
	v_mul_f32_e32 v24, v24, v56
	v_mul_f32_e32 v25, v25, v57
	v_mul_f32_e32 v28, v28, v58
	v_mul_f32_e32 v29, v29, v59
	s_waitcnt vmcnt(7)
	v_mov_b32_e32 v54, v47
	s_waitcnt vmcnt(6)
	v_mov_b32_e32 v55, v46
	s_waitcnt vmcnt(5)
	v_mov_b32_e32 v56, v43
	s_waitcnt vmcnt(4)
	v_mov_b32_e32 v57, v42
	s_waitcnt vmcnt(3)
	v_mov_b32_e32 v58, v49
	s_waitcnt vmcnt(2)
	v_mov_b32_e32 v59, v48
	v_mul_f32_e32 v50, v0, v46
	v_mul_f32_e32 v51, v1, v47
	v_mul_f32_e32 v46, v8, v42
	v_mul_f32_e32 v47, v9, v43
	v_mul_f32_e32 v42, v24, v48
	v_mul_f32_e32 v43, v25, v49
	s_waitcnt vmcnt(1)
	v_mov_b32_e32 v60, v53
	s_waitcnt vmcnt(0)
	v_mov_b32_e32 v61, v52
	v_mul_f32_e32 v48, v28, v52
	v_mul_f32_e32 v49, v29, v53
	v_mul_f32_e32 v0, v0, v54
	v_mul_f32_e32 v1, v1, v55
	v_mul_f32_e32 v8, v8, v56
	v_mul_f32_e32 v9, v9, v57
	v_mul_f32_e32 v24, v24, v58
	v_mul_f32_e32 v25, v25, v59
	v_mul_f32_e32 v28, v28, v60
	v_mul_f32_e32 v29, v29, v61
	v_or_b32_e32 v52, 0x1100, v144
	v_mov_b32_e32 v53, v145
	v_lshl_add_u64 v[54:55], s[6:7], 0, v[52:53]
	v_lshl_add_u64 v[52:53], s[8:9], 0, v[52:53]
	global_load_dword v60, v[54:55], off
	global_load_dword v61, v[52:53], off
	v_or_b32_e32 v52, 0x1140, v144
	v_mov_b32_e32 v53, v145
	v_or_b32_e32 v56, 0x1180, v144
	v_mov_b32_e32 v57, v145
	v_lshl_add_u64 v[54:55], s[6:7], 0, v[52:53]
	v_lshl_add_u64 v[52:53], s[8:9], 0, v[52:53]
	v_lshl_add_u64 v[58:59], s[6:7], 0, v[56:57]
	v_lshl_add_u64 v[56:57], s[8:9], 0, v[56:57]
	global_load_dword v62, v[54:55], off
	global_load_dword v63, v[52:53], off
	s_nop 0
	global_load_dword v58, v[58:59], off
	s_nop 0
	global_load_dword v56, v[56:57], off
	v_or_b32_e32 v52, 0x11c0, v144
	v_mov_b32_e32 v53, v145
	v_lshl_add_u64 v[54:55], s[6:7], 0, v[52:53]
	v_lshl_add_u64 v[52:53], s[8:9], 0, v[52:53]
	global_load_dword v57, v[54:55], off
	global_load_dword v59, v[52:53], off
	v_mov_b32_e32 v52, v51
	v_mov_b32_e32 v40, v1
	v_mov_b32_e32 v44, v9
	v_mov_b32_e32 v4, v25
	v_mov_b32_e32 v16, v49
	v_mov_b32_e32 v20, v47
	v_mov_b32_e32 v54, v43
	v_mov_b32_e32 v12, v29
	s_waitcnt vmcnt(7)
	v_mul_f32_e32 v53, v41, v60
	s_waitcnt vmcnt(6)
	v_mul_f32_e32 v51, v21, v61
	v_mul_f32_e32 v41, v41, v61
	v_mul_f32_e32 v1, v21, v60
	v_add_f32_e32 v0, v0, v40
	v_add_f32_e32 v1, v1, v41
	s_waitcnt vmcnt(5)
	v_mul_f32_e32 v21, v45, v62
	s_waitcnt vmcnt(4)
	v_mul_f32_e32 v45, v45, v63
	v_mul_f32_e32 v9, v109, v62
	s_waitcnt vmcnt(3)
	v_mul_f32_e32 v55, v5, v58
	s_waitcnt vmcnt(2)
	v_mul_f32_e32 v49, v17, v56
	v_mul_f32_e32 v5, v5, v56
	v_mul_f32_e32 v25, v17, v58
	v_mul_f32_e32 v47, v109, v63
	s_waitcnt vmcnt(0)
	v_mul_f32_e32 v56, v110, v59
	v_mul_f32_e32 v17, v13, v57
	v_mul_f32_e32 v13, v13, v59
	v_mul_f32_e32 v29, v110, v57
	v_add_f32_e32 v8, v8, v44
	v_add_f32_e32 v9, v9, v45
	v_mov_b32_e32 v43, v49
	v_add_f32_e32 v4, v24, v4
	v_add_f32_e32 v5, v25, v5
	v_mov_b32_e32 v49, v56
	v_add_f32_e32 v12, v28, v12
	v_add_f32_e32 v13, v29, v13
	v_add_f32_e64 v24, v52, -v50
	v_add_f32_e64 v25, v53, -v51
	v_mul_f32_e32 v116, v64, v0
	v_mul_f32_e32 v117, v64, v1
	v_add_f32_e64 v0, v20, -v46
	v_add_f32_e64 v1, v21, -v47
	v_mul_f32_e32 v118, v64, v8
	v_mul_f32_e32 v119, v64, v9
	v_add_f32_e64 v8, v54, -v42
	v_add_f32_e64 v9, v55, -v43
	v_mul_f32_e32 v122, v64, v4
	v_mul_f32_e32 v123, v64, v5
	v_add_f32_e64 v4, v16, -v48
	v_add_f32_e64 v5, v17, -v49
	v_mul_f32_e32 v108, v64, v24
	v_mul_f32_e32 v109, v64, v25
	v_mul_f32_e32 v110, v64, v0
	v_mul_f32_e32 v111, v64, v1
	v_mul_f32_e32 v112, v64, v8
	v_mul_f32_e32 v113, v64, v9
	v_mul_f32_e32 v114, v64, v4
	v_mul_f32_e32 v115, v64, v5
	v_mul_f32_e32 v126, v64, v12
	v_mul_f32_e32 v127, v64, v13
	v_or_b32_e32 v0, 0x1200, v144
	v_mov_b32_e32 v1, v145
	v_or_b32_e32 v8, 0x1240, v144
	v_mov_b32_e32 v9, v145
	v_lshl_add_u64 v[4:5], s[6:7], 0, v[0:1]
	v_lshl_add_u64 v[0:1], s[8:9], 0, v[0:1]
	v_lshl_add_u64 v[12:13], s[6:7], 0, v[8:9]
	v_lshl_add_u64 v[8:9], s[8:9], 0, v[8:9]
	v_or_b32_e32 v16, 0x1280, v144
	v_mov_b32_e32 v17, v145
	v_lshl_add_u64 v[20:21], s[6:7], 0, v[16:17]
	v_lshl_add_u64 v[16:17], s[8:9], 0, v[16:17]
	global_load_dword v5, v[4:5], off
	s_nop 0
	global_load_dword v4, v[0:1], off
	s_nop 0
	global_load_dword v1, v[12:13], off
	global_load_dword v0, v[8:9], off
	s_nop 0
	global_load_dword v9, v[20:21], off
	global_load_dword v8, v[16:17], off
	v_or_b32_e32 v12, 0x12c0, v144
	v_mov_b32_e32 v13, v145
	v_lshl_add_u64 v[16:17], s[6:7], 0, v[12:13]
	v_lshl_add_u64 v[12:13], s[8:9], 0, v[12:13]
	global_load_dword v17, v[16:17], off
	s_nop 0
	global_load_dword v16, v[12:13], off
	v_mul_f32_e32 v12, v148, v142
	v_mul_f32_e32 v13, v148, v143
	v_mov_b32_e32 v20, v2
	v_mov_b32_e32 v21, v6
	v_mul_f32_e32 v24, v148, v140
	v_mul_f32_e32 v25, v148, v141
	v_mov_b32_e32 v28, v10
	v_mov_b32_e32 v29, v14
	v_mul_f32_e32 v40, v148, v124
	v_mul_f32_e32 v41, v148, v125
	v_mov_b32_e32 v42, v26
	v_mov_b32_e32 v43, v18
	v_mul_f32_e32 v44, v148, v120
	v_mul_f32_e32 v45, v148, v121
	v_mov_b32_e32 v46, v30
	v_mov_b32_e32 v47, v22
	v_mul_f32_e32 v12, v20, v12
	v_mul_f32_e32 v13, v21, v13
	v_mul_f32_e32 v20, v28, v24
	v_mul_f32_e32 v21, v29, v25
	v_mul_f32_e32 v24, v42, v40
	v_mul_f32_e32 v25, v43, v41
	v_mul_f32_e32 v28, v46, v44
	v_mul_f32_e32 v29, v47, v45
	s_waitcnt vmcnt(7)
	v_mov_b32_e32 v42, v5
	s_waitcnt vmcnt(6)
	v_mov_b32_e32 v43, v4
	s_waitcnt vmcnt(5)
	v_mov_b32_e32 v44, v1
	s_waitcnt vmcnt(4)
	v_mov_b32_e32 v45, v0
	s_waitcnt vmcnt(3)
	v_mov_b32_e32 v46, v9
	s_waitcnt vmcnt(2)
	v_mov_b32_e32 v47, v8
	v_mul_f32_e32 v40, v12, v4
	v_mul_f32_e32 v41, v13, v5
	v_mul_f32_e32 v4, v20, v0
	v_mul_f32_e32 v5, v21, v1
	v_mul_f32_e32 v0, v24, v8
	v_mul_f32_e32 v1, v25, v9
	s_waitcnt vmcnt(1)
	v_mov_b32_e32 v48, v17
	s_waitcnt vmcnt(0)
	v_mov_b32_e32 v49, v16
	v_mul_f32_e32 v8, v28, v16
	v_mul_f32_e32 v9, v29, v17
	v_mul_f32_e32 v12, v12, v42
	v_mul_f32_e32 v13, v13, v43
	v_mul_f32_e32 v16, v20, v44
	v_mul_f32_e32 v17, v21, v45
	v_mul_f32_e32 v20, v24, v46
	v_mul_f32_e32 v21, v25, v47
	v_mul_f32_e32 v24, v28, v48
	v_mul_f32_e32 v25, v29, v49
	v_or_b32_e32 v28, 0x1300, v144
	v_mov_b32_e32 v29, v145
	v_or_b32_e32 v44, 0x1340, v144
	v_mov_b32_e32 v45, v145
	v_lshl_add_u64 v[42:43], s[6:7], 0, v[28:29]
	v_lshl_add_u64 v[28:29], s[8:9], 0, v[28:29]
	v_lshl_add_u64 v[46:47], s[6:7], 0, v[44:45]
	v_lshl_add_u64 v[44:45], s[8:9], 0, v[44:45]
	v_or_b32_e32 v48, 0x1380, v144
	v_mov_b32_e32 v49, v145
	v_or_b32_e32 v144, 0x13c0, v144
	v_lshl_add_u64 v[50:51], s[6:7], 0, v[48:49]
	v_lshl_add_u64 v[48:49], s[8:9], 0, v[48:49]
	global_load_dword v42, v[42:43], off
	s_nop 0
	global_load_dword v43, v[28:29], off
	s_nop 0
	global_load_dword v28, v[46:47], off
	global_load_dword v29, v[44:45], off
	s_nop 0
	global_load_dword v44, v[50:51], off
	global_load_dword v45, v[48:49], off
	v_lshl_add_u64 v[46:47], s[6:7], 0, v[144:145]
	v_lshl_add_u64 v[48:49], s[8:9], 0, v[144:145]
	global_load_dword v46, v[46:47], off
	s_nop 0
	global_load_dword v47, v[48:49], off
	v_mul_f32_e32 v32, v32, v146
	v_mul_f32_e32 v33, v33, v146
	v_mov_b32_e32 v2, v7
	v_mul_f32_e32 v34, v34, v146
	v_mul_f32_e32 v35, v35, v146
	v_mov_b32_e32 v10, v15
	v_mul_f32_e32 v36, v36, v146
	v_mul_f32_e32 v37, v37, v146
	v_mov_b32_e32 v26, v19
	v_mul_f32_e32 v38, v38, v146
	v_mul_f32_e32 v39, v39, v146
	v_mov_b32_e32 v30, v23
	v_mul_f32_e32 v2, v2, v32
	v_mul_f32_e32 v3, v3, v33
	v_mul_f32_e32 v10, v10, v34
	v_mul_f32_e32 v11, v11, v35
	v_mul_f32_e32 v26, v26, v36
	v_mul_f32_e32 v27, v27, v37
	v_mul_f32_e32 v30, v30, v38
	v_mul_f32_e32 v31, v31, v39
	v_mov_b32_e32 v6, v12
	v_mov_b32_e32 v14, v16
	v_mov_b32_e32 v18, v20
	v_mov_b32_e32 v22, v24
	s_waitcnt vmcnt(7)
	v_mov_b32_e32 v35, v42
	s_waitcnt vmcnt(6)
	v_mul_f32_e32 v32, v2, v42
	v_mul_f32_e32 v33, v3, v43
	v_mov_b32_e32 v34, v43
	s_waitcnt vmcnt(4)
	v_mul_f32_e32 v36, v10, v28
	v_mul_f32_e32 v37, v11, v29
	v_mov_b32_e32 v38, v29
	v_mov_b32_e32 v39, v28
	s_waitcnt vmcnt(2)
	v_mul_f32_e32 v28, v26, v44
	v_mul_f32_e32 v29, v27, v45
	v_mov_b32_e32 v42, v45
	v_mov_b32_e32 v43, v44
	s_waitcnt vmcnt(0)
	v_mov_b32_e32 v48, v47
	v_mov_b32_e32 v49, v46
	v_mul_f32_e32 v44, v30, v46
	v_mul_f32_e32 v45, v31, v47
	v_pk_mov_b32 v[46:47], v[40:41], v[32:33] op_sel:[1,0]
	v_mov_b32_e32 v41, v33
	v_mul_f32_e32 v2, v2, v34
	v_mul_f32_e32 v3, v3, v35
	v_pk_mov_b32 v[32:33], v[4:5], v[36:37] op_sel:[1,0]
	v_mov_b32_e32 v5, v37
	v_mul_f32_e32 v10, v10, v38
	v_mul_f32_e32 v11, v11, v39
	v_pk_mov_b32 v[34:35], v[0:1], v[28:29] op_sel:[1,0]
	v_mov_b32_e32 v1, v29
	v_mul_f32_e32 v26, v26, v42
	v_mul_f32_e32 v27, v27, v43
	v_mul_f32_e32 v30, v30, v48
	v_mul_f32_e32 v31, v31, v49
	v_pk_mov_b32 v[28:29], v[8:9], v[44:45] op_sel:[1,0]
	v_mov_b32_e32 v9, v45
	v_mov_b32_e32 v7, v3
	v_pk_mov_b32 v[2:3], v[12:13], v[2:3] op_sel:[1,0]
	v_add_f32_e64 v4, v32, -v4
	v_add_f32_e64 v5, v33, -v5
	v_mov_b32_e32 v15, v11
	v_pk_mov_b32 v[10:11], v[16:17], v[10:11] op_sel:[1,0]
	v_add_f32_e64 v0, v34, -v0
	v_add_f32_e64 v1, v35, -v1
	v_mov_b32_e32 v19, v27
	v_pk_mov_b32 v[12:13], v[20:21], v[26:27] op_sel:[1,0]
	v_mov_b32_e32 v23, v31
	v_pk_mov_b32 v[16:17], v[24:25], v[30:31] op_sel:[1,0]
	v_add_f32_e64 v36, v46, -v40
	v_add_f32_e64 v37, v47, -v41
	v_add_f32_e64 v8, v28, -v8
	v_add_f32_e64 v9, v29, -v9
	v_add_f32_e32 v2, v6, v2
	v_add_f32_e32 v3, v7, v3
	v_mul_f32_e32 v124, v64, v4
	v_mul_f32_e32 v125, v64, v5
	v_add_f32_e32 v4, v14, v10
	v_add_f32_e32 v5, v15, v11
	v_mul_f32_e32 v140, v64, v0
	v_mul_f32_e32 v141, v64, v1
	v_add_f32_e32 v0, v18, v12
	v_add_f32_e32 v1, v19, v13
	v_add_f32_e32 v6, v22, v16
	v_add_f32_e32 v7, v23, v17
	v_mul_f32_e32 v120, v64, v36
	v_mul_f32_e32 v121, v64, v37
	v_mul_f32_e32 v142, v64, v8
	v_mul_f32_e32 v143, v64, v9
	v_mul_f32_e32 v144, v64, v2
	v_mul_f32_e32 v145, v64, v3
	v_mul_f32_e32 v146, v64, v4
	v_mul_f32_e32 v147, v64, v5
	v_mul_f32_e32 v148, v64, v0
	v_mul_f32_e32 v149, v64, v1
	v_mul_f32_e32 v150, v64, v6
	v_mul_f32_e32 v151, v64, v7
	s_and_b64 s[0:1], s[56:57], exec
	s_cselect_b32 s0, s61, 0xba00000
	s_add_u32 s4, s50, s0
	s_addc_u32 s5, s51, 0
	s_lshl_b64 s[0:1], s[54:55], 1
	s_add_u32 s0, s4, s0
	s_addc_u32 s1, s5, s1
	s_lshl_b32 s4, s33, 8
	s_add_u32 s56, s0, s4
	s_addc_u32 s57, s1, 0
	s_cbranch_execnz .LBB0_441
